# norm_mod loops software-pipelined: next step's 4 rows prefetched into spare VGPRs while computing current
# speedup vs baseline: 1.0049x; 1.0049x over previous
; __device__ __forceinline__ void norm_mod_phase(const float* x, const float* x0src, size_t x0stride, float* h0buf, const float* g, const float* sh, const float* sc, bf16* XN, int gw, int NGW, int lane) {
;     const int wpb = NGW / BATCH, rpw = T / wpb;
;     const int b = gw / wpb, wi = gw - b * wpb;
;     f32x4 gm[4], s0[4];
; #pragma unroll
;     for (int j = 0; j < 4; ++j) { const int col = 4 * lane + 256 * j; gm[j] = *(const f32x4*)(g + col) * (*(const f32x4*)(sc + b * NMOD + col) + 1.f); s0[j] = *(const f32x4*)(sh + b * NMOD + col); }
;     for (int k = 0; k < rpw; k += 4) {
.LBB0_161:
	s_abs_i32 s18, s19
	v_cvt_f32_u32_e32 v1, s18
	v_readlane_b32 s5, v255, 2
	s_ashr_i32 s20, s19, 31
	v_rcp_iflag_f32_e32 v1, v1
	v_mov_b32_e32 v2, s5
	s_sub_i32 s5, 0, s18
	ds_read_b64 v[2:3], v2
	v_mul_f32_e32 v1, 0x4f7ffffe, v1
	v_cvt_u32_f32_e32 v1, v1
	s_waitcnt lgkmcnt(0)
	v_readfirstlane_b32 s64, v2
	v_readfirstlane_b32 s65, v1
	s_mul_i32 s5, s5, s65
	s_mul_hi_u32 s5, s65, s5
	s_add_i32 s65, s65, s5
	s_lshr_b32 s5, s65, 20
	s_mul_i32 s8, s5, s18
	s_sub_i32 s8, 0x1000, s8
	s_add_i32 s9, s5, 1
	s_sub_i32 s12, s8, s18
	s_cmp_ge_u32 s8, s18
	s_cselect_b32 s5, s9, s5
	s_cselect_b32 s8, s12, s8
	s_add_i32 s9, s5, 1
	s_cmp_ge_u32 s8, s18
	s_cselect_b32 s5, s9, s5
	s_xor_b32 s5, s5, s20
	s_sub_i32 s8, s5, s20
	s_cmp_lt_i32 s8, 1
	v_readfirstlane_b32 s66, v3
	s_cbranch_scc1 .LBB0_196
	s_mul_i32 s12, s62, 0xc000
	s_ashr_i32 s5, s7, 6
	s_lshl_b32 s9, s6, 3
	s_lshl_b32 s68, s62, 10
	s_add_i32 s67, s5, s9
	s_lshl_b64 s[6:7], s[12:13], 2
	s_mov_b32 s69, s13
	s_add_u32 s12, s61, s6
	s_addc_u32 s70, s63, s7
	s_lshl_b64 s[6:7], s[68:69], 2
	s_add_u32 s68, s64, s6
	s_addc_u32 s69, s66, s7
	s_ashr_i32 s6, s67, 31
	s_xor_b32 s64, s6, s20
	s_abs_i32 s6, s67
	s_mul_hi_u32 s7, s6, s65
	s_mul_i32 s20, s7, s18
	s_sub_i32 s6, s6, s20
	s_add_i32 s20, s7, 1
	s_sub_i32 s65, s6, s18
	s_cmp_ge_u32 s6, s18
	s_cselect_b32 s7, s20, s7
	s_cselect_b32 s6, s65, s6
	s_add_i32 s20, s7, 1
	s_cmp_ge_u32 s6, s18
	s_cselect_b32 s6, s20, s7
	s_xor_b32 s65, s6, s64
	s_sub_i32 s6, s65, s64
	s_mul_i32 s66, s6, 0x1800
	s_ashr_i32 s67, s66, 31
	s_lshl_b64 s[66:67], s[66:67], 2
	v_and_b32_e32 v16, 63, v0
	s_add_u32 s66, s12, s66
	s_addc_u32 s67, s70, s67
	v_lshlrev_b32_e32 v162, 4, v16
	v_lshl_add_u64 v[0:1], s[66:67], 0, v[162:163]
	v_add_co_u32_e32 v2, vcc, s46, v0
	s_mov_b64 s[34:35], 0x1000
	s_nop 0
	v_addc_co_u32_e32 v3, vcc, 0, v1, vcc
	global_load_dwordx4 v[18:21], v[2:3], off
	v_lshl_add_u64 v[0:1], v[0:1], 0, s[34:35]
	global_load_dwordx4 v[22:25], v[0:1], off offset:1024
	global_load_dwordx4 v[26:29], v[0:1], off offset:2048
	global_load_dwordx4 v[30:33], v[0:1], off offset:3072
	global_load_dwordx4 v[34:37], v162, s[68:69]
	global_load_dwordx4 v[38:41], v162, s[68:69] offset:1024
	global_load_dwordx4 v[42:45], v162, s[68:69] offset:2048
	global_load_dwordx4 v[46:49], v162, s[68:69] offset:3072
	s_nop 0
	global_load_dwordx4 v[0:3], v162, s[66:67]
	global_load_dwordx4 v[4:7], v162, s[66:67] offset:1024
	global_load_dwordx4 v[8:11], v162, s[66:67] offset:2048
	global_load_dwordx4 v[12:15], v162, s[66:67] offset:3072
	s_ashr_i32 s7, s6, 31
	s_lshl_b64 s[68:69], s[6:7], 24
	s_mul_hi_i32 s67, s4, s6
	s_mul_i32 s66, s4, s6
	s_add_u32 s16, s16, s68
	s_addc_u32 s17, s17, s69
	s_lshl_b64 s[66:67], s[66:67], 2
	s_add_u32 s18, s0, s66
	s_addc_u32 s20, s1, s67
	s_lshl_b64 s[0:1], s[6:7], 23
	s_add_u32 s0, s61, s0
	s_mul_i32 s70, s6, s19
	s_addc_u32 s1, s63, s1
	s_lshl_b32 s6, s6, 10
	s_ashr_i32 s7, s6, 31
	s_lshl_b64 s[6:7], s[6:7], 2
	s_add_u32 s6, s61, s6
	s_addc_u32 s7, s63, s7
	v_cmp_lt_i32_e32 vcc, v228, v222
	v_xor_b32_e32 v50, 2, v221
	s_lshl_b32 s63, s19, 2
	v_cndmask_b32_e32 v17, v221, v228, vcc
	v_cmp_lt_i32_e32 vcc, v50, v222
	s_mov_b32 s12, 0
	v_lshlrev_b32_e32 v104, 2, v17
	v_cndmask_b32_e32 v50, v221, v50, vcc
	v_cmp_lt_i32_e32 vcc, v218, v222
	v_lshlrev_b32_e32 v105, 2, v50
	s_sub_i32 s78, s5, s70
	v_cndmask_b32_e32 v51, v221, v218, vcc
	v_cmp_lt_i32_e32 vcc, v219, v222
	v_lshlrev_b32_e32 v106, 2, v51
	v_lshlrev_b32_e32 v110, 4, v16
	v_cndmask_b32_e32 v52, v221, v219, vcc
	v_cmp_lt_i32_e32 vcc, v254, v222
	v_lshlrev_b32_e32 v107, 2, v52
	s_waitcnt vmcnt(0)
	v_pk_add_f32 v[24:25], v[24:25], 1.0 op_sel_hi:[1,0]
	v_cndmask_b32_e32 v53, v221, v254, vcc
	v_cmp_lt_i32_e32 vcc, v223, v222
	v_pk_add_f32 v[22:23], v[22:23], 1.0 op_sel_hi:[1,0]
	s_waitcnt vmcnt(9)
	v_pk_add_f32 v[28:29], v[28:29], 1.0 op_sel_hi:[1,0]
	v_cndmask_b32_e32 v54, v221, v223, vcc
	v_pk_add_f32 v[26:27], v[26:27], 1.0 op_sel_hi:[1,0]
	s_waitcnt vmcnt(8)
	v_pk_add_f32 v[32:33], v[32:33], 1.0 op_sel_hi:[1,0]
	v_pk_add_f32 v[18:19], v[18:19], 1.0 op_sel_hi:[1,0]
	v_pk_add_f32 v[20:21], v[20:21], 1.0 op_sel_hi:[1,0]
	s_waitcnt vmcnt(7)
	v_pk_mul_f32 v[82:83], v[34:35], v[18:19]
	v_lshl_add_u64 v[18:19], s[6:7], 0, v[162:163]
	s_mov_b64 s[6:7], 0x598000
	v_lshlrev_b32_e32 v162, 3, v16
	v_lshl_add_u64 v[96:97], v[18:19], 0, s[6:7]
	v_lshl_add_u64 v[18:19], s[0:1], 0, v[162:163]
	s_mov_b64 s[0:1], 0x6e00000
	v_lshl_add_u64 v[98:99], v[18:19], 0, s[0:1]
	s_sub_i32 s0, s64, s65
	s_add_i32 s1, s0, 1
	s_mul_i32 s1, s19, s1
	s_add_i32 s61, s5, s1
	s_add_i32 s1, s0, 2
	s_add_i32 s0, s0, 3
	v_pk_add_f32 v[30:31], v[30:31], 1.0 op_sel_hi:[1,0]
	s_mul_i32 s1, s19, s1
	s_mul_i32 s19, s19, s0
	v_lshlrev_b32_e32 v108, 2, v53
	v_lshlrev_b32_e32 v109, 2, v54
	v_pk_mul_f32 v[80:81], v[36:37], v[20:21]
	s_waitcnt vmcnt(6)
	v_pk_mul_f32 v[84:85], v[40:41], v[24:25]
	v_pk_mul_f32 v[86:87], v[38:39], v[22:23]
	s_waitcnt vmcnt(5)
	v_pk_mul_f32 v[88:89], v[44:45], v[28:29]
	v_pk_mul_f32 v[90:91], v[42:43], v[26:27]
	s_waitcnt vmcnt(4)
	v_pk_mul_f32 v[92:93], v[48:49], v[32:33]
	v_pk_mul_f32 v[94:95], v[46:47], v[30:31]
	s_add_i32 s76, s5, s1
	s_add_i32 s77, s5, s19
	s_lshl_b32 s98, s63, 10
	s_mul_i32 s99, s98, 3
	v_add_u32_e32 v198, s99, v110
	s_add_i32 s99, s99, s98
	v_add_u32_e32 v199, s99, v110
	s_add_i32 s99, s99, s98
	v_add_u32_e32 v200, s99, v110
	s_add_i32 s99, s99, s98
	v_add_u32_e32 v201, s99, v110
	s_branch .LBB0_164

; __device__ __forceinline__ void norm_mod_phase(const float* x, const float* x0src, size_t x0stride, float* h0buf, const float* g, const float* sh, const float* sc, bf16* XN, int gw, int NGW, int lane) {
;     ...
;     for (int k = 0; k < rpw; k += 4) {
;         f32x4 v[4][4];
; #pragma unroll
;         for (int r = 0; r < 4; ++r) { const int t = wi + wpb * (k + r); const bool t0 = t == 0;
;             const f32x4* xr = (const f32x4*)(t0 ? x0src + (size_t)b * x0stride : x + ((size_t)b * T + t) * D) + lane;
; #pragma unroll
;             for (int j = 0; j < 4; ++j) v[r][j] = xr[64 * j]; }
.LBB0_164:
	s_add_i32 s0, s9, s78
	s_ashr_i32 s1, s0, 31
	s_lshl_b64 s[4:5], s[0:1], 12
	s_add_u32 s6, s16, s4
	s_addc_u32 s7, s17, s5
	s_cmp_eq_u32 s0, 0
	s_cselect_b64 s[72:73], -1, 0
	s_and_b64 s[4:5], s[72:73], exec
	s_cselect_b32 s74, s18, s6
	s_cselect_b32 s75, s20, s7
	s_add_i32 s70, s9, s61
	s_ashr_i32 s71, s70, 31
	s_lshl_b64 s[4:5], s[70:71], 12
	s_add_u32 s6, s16, s4
	s_addc_u32 s7, s17, s5
	s_cmp_eq_u32 s70, 0
	s_cselect_b64 s[68:69], -1, 0
	s_and_b64 s[4:5], s[68:69], exec
	s_cselect_b32 s80, s18, s6
	s_cselect_b32 s81, s20, s7
	s_add_i32 s66, s9, s76
	s_ashr_i32 s67, s66, 31
	s_lshl_b64 s[4:5], s[66:67], 12
	s_add_u32 s6, s16, s4
	s_addc_u32 s7, s17, s5
	s_cmp_eq_u32 s66, 0
	s_cselect_b64 s[64:65], -1, 0
	s_and_b64 s[4:5], s[64:65], exec
	s_cselect_b32 s82, s18, s6
	s_cselect_b32 s83, s20, s7
	s_add_i32 s6, s9, s77
	s_ashr_i32 s7, s6, 31
	s_lshl_b64 s[4:5], s[6:7], 12
	s_add_u32 s19, s16, s4
	s_addc_u32 s79, s17, s5
	s_cmp_eq_u32 s6, 0
	s_cselect_b64 s[4:5], -1, 0
	s_and_b64 s[84:85], s[4:5], exec
	s_cselect_b32 s84, s18, s19
	s_cselect_b32 s85, s20, s79
	s_cmp_lg_u32 s12, 0
	s_cbranch_scc1 .Lnp1_rest
	global_load_dwordx4 v[76:79], v110, s[74:75]
	global_load_dwordx4 v[72:75], v110, s[74:75] offset:1024
	global_load_dwordx4 v[68:71], v110, s[74:75] offset:2048
	global_load_dwordx4 v[64:67], v110, s[74:75] offset:3072
	global_load_dwordx4 v[60:63], v110, s[80:81]
	global_load_dwordx4 v[56:59], v110, s[80:81] offset:1024
	global_load_dwordx4 v[52:55], v110, s[80:81] offset:2048
	global_load_dwordx4 v[48:51], v110, s[80:81] offset:3072
	global_load_dwordx4 v[44:47], v110, s[82:83]
	global_load_dwordx4 v[40:43], v110, s[82:83] offset:1024
	global_load_dwordx4 v[36:39], v110, s[82:83] offset:2048
	global_load_dwordx4 v[32:35], v110, s[82:83] offset:3072
	global_load_dwordx4 v[28:31], v110, s[84:85]
	global_load_dwordx4 v[24:27], v110, s[84:85] offset:1024
	global_load_dwordx4 v[20:23], v110, s[84:85] offset:2048
	global_load_dwordx4 v[16:19], v110, s[84:85] offset:3072
	s_add_i32 s99, s12, 4
	s_cmp_lt_i32 s99, s8
	s_cbranch_scc0 .Lnp1_first_nopf
	global_load_dwordx4 v[194:197], v198, s[80:81]
	global_load_dwordx4 v[190:193], v198, s[80:81] offset:1024
	global_load_dwordx4 v[186:189], v198, s[80:81] offset:2048
	global_load_dwordx4 v[182:185], v198, s[80:81] offset:3072
	global_load_dwordx4 v[178:181], v199, s[80:81]
	global_load_dwordx4 v[156:159], v199, s[80:81] offset:1024
	global_load_dwordx4 v[152:155], v199, s[80:81] offset:2048
	global_load_dwordx4 v[148:151], v199, s[80:81] offset:3072
	global_load_dwordx4 v[144:147], v200, s[80:81]
	global_load_dwordx4 v[140:143], v200, s[80:81] offset:1024
	global_load_dwordx4 v[136:139], v200, s[80:81] offset:2048
	global_load_dwordx4 v[132:135], v200, s[80:81] offset:3072
	global_load_dwordx4 v[128:131], v201, s[80:81]
	global_load_dwordx4 v[124:127], v201, s[80:81] offset:1024
	global_load_dwordx4 v[120:123], v201, s[80:81] offset:2048
	global_load_dwordx4 v[116:119], v201, s[80:81] offset:3072
	s_waitcnt vmcnt(16)
	s_branch .Lnp1_go
.Lnp1_first_nopf:
	s_waitcnt vmcnt(0)
	s_branch .Lnp1_go
.Lnp1_rest:
	s_waitcnt vmcnt(16)
	v_mov_b64_e32 v[16:17], v[116:117]
	v_mov_b64_e32 v[18:19], v[118:119]
	v_mov_b64_e32 v[20:21], v[120:121]
	v_mov_b64_e32 v[22:23], v[122:123]
	v_mov_b64_e32 v[24:25], v[124:125]
	v_mov_b64_e32 v[26:27], v[126:127]
	v_mov_b64_e32 v[28:29], v[128:129]
	v_mov_b64_e32 v[30:31], v[130:131]
	v_mov_b64_e32 v[32:33], v[132:133]
	v_mov_b64_e32 v[34:35], v[134:135]
	v_mov_b64_e32 v[36:37], v[136:137]
	v_mov_b64_e32 v[38:39], v[138:139]
	v_mov_b64_e32 v[40:41], v[140:141]
	v_mov_b64_e32 v[42:43], v[142:143]
	v_mov_b64_e32 v[44:45], v[144:145]
	v_mov_b64_e32 v[46:47], v[146:147]
	v_mov_b64_e32 v[48:49], v[148:149]
	v_mov_b64_e32 v[50:51], v[150:151]
	v_mov_b64_e32 v[52:53], v[152:153]
	v_mov_b64_e32 v[54:55], v[154:155]
	v_mov_b64_e32 v[56:57], v[156:157]
	v_mov_b64_e32 v[58:59], v[158:159]
	v_mov_b64_e32 v[60:61], v[178:179]
	v_mov_b64_e32 v[62:63], v[180:181]
	v_mov_b64_e32 v[64:65], v[182:183]
	v_mov_b64_e32 v[66:67], v[184:185]
	v_mov_b64_e32 v[68:69], v[186:187]
	v_mov_b64_e32 v[70:71], v[188:189]
	v_mov_b64_e32 v[72:73], v[190:191]
	v_mov_b64_e32 v[74:75], v[192:193]
	v_mov_b64_e32 v[76:77], v[194:195]
	v_mov_b64_e32 v[78:79], v[196:197]
	s_add_i32 s99, s12, 4
	s_cmp_lt_i32 s99, s8
	s_cbranch_scc0 .Lnp1_go
	global_load_dwordx4 v[194:197], v198, s[80:81]
	global_load_dwordx4 v[190:193], v198, s[80:81] offset:1024
	global_load_dwordx4 v[186:189], v198, s[80:81] offset:2048
	global_load_dwordx4 v[182:185], v198, s[80:81] offset:3072
	global_load_dwordx4 v[178:181], v199, s[80:81]
	global_load_dwordx4 v[156:159], v199, s[80:81] offset:1024
	global_load_dwordx4 v[152:155], v199, s[80:81] offset:2048
	global_load_dwordx4 v[148:151], v199, s[80:81] offset:3072
	global_load_dwordx4 v[144:147], v200, s[80:81]
	global_load_dwordx4 v[140:143], v200, s[80:81] offset:1024
	global_load_dwordx4 v[136:139], v200, s[80:81] offset:2048
	global_load_dwordx4 v[132:135], v200, s[80:81] offset:3072
	global_load_dwordx4 v[128:131], v201, s[80:81]
	global_load_dwordx4 v[124:127], v201, s[80:81] offset:1024
	global_load_dwordx4 v[120:123], v201, s[80:81] offset:2048
	global_load_dwordx4 v[116:119], v201, s[80:81] offset:3072
; __device__ __forceinline__ unsigned pk2(float lo, float hi) { return f2bf(lo) | (f2bf(hi) << 16); }
; __device__ __forceinline__ void norm_mod_phase(const float* x, const float* x0src, size_t x0stride, float* h0buf, const float* g, const float* sh, const float* sc, bf16* XN, int gw, int NGW, int lane) {
;     ...
;         for (int r = 0; r < 4; ++r) { const int t = wi + wpb * (k + r); const bool t0 = t == 0; const size_t row = (size_t)b * T + t;
;             float ss = 0.f;
; #pragma unroll
;             for (int j = 0; j < 4; ++j) ss += (v[r][j].x * v[r][j].x + v[r][j].y * v[r][j].y) + (v[r][j].z * v[r][j].z + v[r][j].w * v[r][j].w);
;             const float rstd = 1.f / sqrtf(wave_sum(ss) * (1.f / D) + EPS);
; #pragma unroll
;             for (int j = 0; j < 4; ++j) { const int col = 4 * lane + 256 * j;
;                 const f32x4 h = v[r][j] * rstd * gm[j] + s0[j];
;                 v2u o; o.x = pk2(h.x, h.y); o.y = pk2(h.z, h.w);
;                 *(v2u*)(XN + row * D + col) = o;
;                 if (t0) *(f32x4*)(h0buf + b * D + col) = h; } }
.Lnp1_go:
	s_lshl_b64 s[74:75], s[0:1], 11
	s_cmp_lg_u32 s0, 0
	s_nop 0
	v_pk_mul_f32 v[100:101], v[78:79], v[78:79]
	v_pk_mul_f32 v[102:103], v[76:77], v[76:77]
	s_nop 0
	v_mul_f32_e32 v111, v64, v64
	v_pk_mov_b32 v[112:113], v[102:103], v[100:101] op_sel:[1,0]
	v_mov_b32_e32 v103, v101
	v_pk_add_f32 v[100:101], v[112:113], v[102:103]
	v_pk_mul_f32 v[102:103], v[74:75], v[74:75]
	v_pk_mul_f32 v[112:113], v[72:73], v[72:73]
	v_pk_add_f32 v[100:101], v[100:101], v[100:101] op_sel:[0,1] op_sel_hi:[1,0]
	v_pk_mov_b32 v[114:115], v[112:113], v[102:103] op_sel:[1,0]
	v_mov_b32_e32 v113, v103
	v_pk_add_f32 v[102:103], v[114:115], v[112:113]
	v_mul_f32_e32 v112, v65, v65
	v_pk_add_f32 v[102:103], v[102:103], v[102:103] op_sel:[0,1] op_sel_hi:[1,0]
	v_mov_b32_e32 v101, v111
	v_mov_b32_e32 v103, v112
	v_pk_add_f32 v[100:101], v[100:101], v[102:103]
	v_mul_f32_e32 v102, v69, v69
	v_mul_f32_e32 v113, v66, v66
	v_pk_fma_f32 v[102:103], v[68:69], v[68:69], v[102:103] op_sel_hi:[1,1,0]
	v_mul_f32_e32 v112, v71, v71
	v_mul_f32_e32 v114, v67, v67
	v_mov_b32_e32 v103, v113
	v_pk_fma_f32 v[112:113], v[70:71], v[70:71], v[112:113] op_sel_hi:[1,1,0]
	s_nop 0
	v_mov_b32_e32 v113, v114
	v_pk_add_f32 v[102:103], v[102:103], v[112:113]
	s_nop 0
	v_pk_add_f32 v[100:101], v[100:101], v[102:103]
	s_nop 0
	v_add_f32_e32 v100, v100, v101
	ds_bpermute_b32 v101, v104, v100
	s_waitcnt lgkmcnt(0)
	v_add_f32_e32 v100, v100, v101
	ds_bpermute_b32 v101, v105, v100
	s_waitcnt lgkmcnt(0)
	v_add_f32_e32 v100, v100, v101
	ds_bpermute_b32 v101, v106, v100
	s_waitcnt lgkmcnt(0)
	v_add_f32_e32 v100, v100, v101
	ds_bpermute_b32 v101, v107, v100
	s_waitcnt lgkmcnt(0)
	v_add_f32_e32 v100, v100, v101
	ds_bpermute_b32 v101, v108, v100
	s_waitcnt lgkmcnt(0)
	v_add_f32_e32 v100, v100, v101
	ds_bpermute_b32 v101, v109, v100
	s_waitcnt lgkmcnt(0)
	v_add_f32_e32 v100, v100, v101
	v_fmamk_f32 v100, v100, 0x3a800000, v161
	v_mul_f32_e32 v101, 0x4f800000, v100
	v_cmp_gt_f32_e32 vcc, s58, v100
	s_nop 1
	v_cndmask_b32_e32 v100, v100, v101, vcc
	v_sqrt_f32_e32 v101, v100
	s_nop 0
	v_add_u32_e32 v102, -1, v101
	v_add_u32_e32 v103, 1, v101
	v_fma_f32 v111, -v102, v101, v100
	v_fma_f32 v112, -v103, v101, v100
	v_cmp_ge_f32_e64 s[0:1], 0, v111
	s_nop 1
	v_cndmask_b32_e64 v101, v101, v102, s[0:1]
	v_cmp_lt_f32_e64 s[0:1], 0, v112
	s_nop 1
	v_cndmask_b32_e64 v101, v101, v103, s[0:1]
	v_mul_f32_e32 v102, 0x37800000, v101
	v_cndmask_b32_e32 v101, v101, v102, vcc
	v_cmp_class_f32_e32 vcc, v100, v177
	s_nop 1
	v_cndmask_b32_e32 v100, v101, v100, vcc
	v_div_scale_f32 v101, s[0:1], v100, v100, 1.0
	v_rcp_f32_e32 v102, v101
	v_div_scale_f32 v103, vcc, 1.0, v100, 1.0
	v_fma_f32 v111, -v101, v102, 1.0
	v_fmac_f32_e32 v102, v111, v102
	v_mul_f32_e32 v111, v103, v102
	v_fma_f32 v112, -v101, v111, v103
	v_fmac_f32_e32 v111, v112, v102
	v_fma_f32 v101, -v101, v111, v103
	v_div_fmas_f32 v101, v101, v102, v111
	v_div_fixup_f32 v100, v101, v100, 1.0
	v_pk_mul_f32 v[76:77], v[76:77], v[100:101] op_sel_hi:[1,0]
	v_pk_mul_f32 v[78:79], v[78:79], v[100:101] op_sel_hi:[1,0]
	v_pk_fma_f32 v[76:77], v[82:83], v[76:77], v[0:1]
	v_pk_fma_f32 v[78:79], v[80:81], v[78:79], v[2:3]
	v_bfe_u32 v101, v76, 16, 1
	v_add3_u32 v101, v76, v101, s59
	v_bfe_u32 v102, v77, 16, 1
	v_lshrrev_b32_e32 v101, 16, v101
	v_add3_u32 v102, v77, v102, s59
	v_and_or_b32 v112, v102, s60, v101
	v_bfe_u32 v101, v78, 16, 1
	v_add3_u32 v101, v78, v101, s59
	v_bfe_u32 v102, v79, 16, 1
	v_lshrrev_b32_e32 v101, 16, v101
	v_add3_u32 v102, v79, v102, s59
	v_and_or_b32 v113, v102, s60, v101
	v_lshl_add_u64 v[102:103], v[98:99], 0, s[74:75]
	global_store_dwordx2 v[102:103], v[112:113], off
	s_cbranch_scc1 .LBB0_166
	global_store_dwordx4 v[96:97], v[76:79], off

; __device__ __forceinline__ unsigned pk2(float lo, float hi) { return f2bf(lo) | (f2bf(hi) << 16); }
; __device__ __forceinline__ void norm_mod_phase(const float* x, const float* x0src, size_t x0stride, float* h0buf, const float* g, const float* sh, const float* sc, bf16* XN, int gw, int NGW, int lane) {
;     ...
;         for (int r = 0; r < 4; ++r) { const int t = wi + wpb * (k + r); const bool t0 = t == 0; const size_t row = (size_t)b * T + t;
;             float ss = 0.f;
; #pragma unroll
;             for (int j = 0; j < 4; ++j) ss += (v[r][j].x * v[r][j].x + v[r][j].y * v[r][j].y) + (v[r][j].z * v[r][j].z + v[r][j].w * v[r][j].w);
;             const float rstd = 1.f / sqrtf(wave_sum(ss) * (1.f / D) + EPS);
; #pragma unroll
;             for (int j = 0; j < 4; ++j) { const int col = 4 * lane + 256 * j;
;                 const f32x4 h = v[r][j] * rstd * gm[j] + s0[j];
;                 v2u o; o.x = pk2(h.x, h.y); o.y = pk2(h.z, h.w);
;                 *(v2u*)(XN + row * D + col) = o;
;                 if (t0) *(f32x4*)(h0buf + b * D + col) = h; } }
.LBB0_172:
	s_nop 0
	s_nop 0
	v_pk_mul_f32 v[64:65], v[62:63], v[62:63]
	v_pk_mul_f32 v[66:67], v[60:61], v[60:61]
	s_nop 0
	v_pk_mov_b32 v[68:69], v[66:67], v[64:65] op_sel:[1,0]
	v_mov_b32_e32 v67, v65
	v_pk_add_f32 v[64:65], v[68:69], v[66:67]
	s_nop 0
	v_pk_mul_f32 v[66:67], v[58:59], v[58:59]
	v_pk_mul_f32 v[68:69], v[56:57], v[56:57]
	v_pk_add_f32 v[64:65], v[64:65], v[64:65] op_sel:[0,1] op_sel_hi:[1,0]
	v_pk_mov_b32 v[70:71], v[68:69], v[66:67] op_sel:[1,0]
	v_mov_b32_e32 v69, v67
	v_pk_add_f32 v[66:67], v[70:71], v[68:69]
	s_nop 0
	v_mul_f32_e32 v68, v48, v48
	v_mul_f32_e32 v69, v49, v49
	v_pk_add_f32 v[66:67], v[66:67], v[66:67] op_sel:[0,1] op_sel_hi:[1,0]
	v_mov_b32_e32 v65, v68
	v_mov_b32_e32 v67, v69
	v_pk_add_f32 v[64:65], v[64:65], v[66:67]
	v_mul_f32_e32 v66, v53, v53
	v_mul_f32_e32 v68, v55, v55
	v_mul_f32_e32 v70, v50, v50
	v_mul_f32_e32 v71, v51, v51
	v_pk_fma_f32 v[66:67], v[52:53], v[52:53], v[66:67] op_sel_hi:[1,1,0]
	v_pk_fma_f32 v[68:69], v[54:55], v[54:55], v[68:69] op_sel_hi:[1,1,0]
	v_mov_b32_e32 v67, v70
	v_mov_b32_e32 v69, v71
	v_pk_add_f32 v[66:67], v[66:67], v[68:69]
	s_nop 0
	v_pk_add_f32 v[64:65], v[64:65], v[66:67]
	s_nop 0
	v_add_f32_e32 v64, v64, v65
	ds_bpermute_b32 v65, v104, v64
	s_waitcnt lgkmcnt(0)
	v_add_f32_e32 v64, v64, v65
	ds_bpermute_b32 v65, v105, v64
	s_waitcnt lgkmcnt(0)
	v_add_f32_e32 v64, v64, v65
	ds_bpermute_b32 v65, v106, v64
	s_waitcnt lgkmcnt(0)
	v_add_f32_e32 v64, v64, v65
	ds_bpermute_b32 v65, v107, v64
	s_waitcnt lgkmcnt(0)
	v_add_f32_e32 v64, v64, v65
	ds_bpermute_b32 v65, v108, v64
	s_waitcnt lgkmcnt(0)
	v_add_f32_e32 v64, v64, v65
	ds_bpermute_b32 v65, v109, v64
	s_waitcnt lgkmcnt(0)
	v_add_f32_e32 v64, v64, v65
	v_fmamk_f32 v64, v64, 0x3a800000, v161
	v_mul_f32_e32 v65, 0x4f800000, v64
	v_cmp_gt_f32_e32 vcc, s58, v64
	s_nop 1
	v_cndmask_b32_e32 v64, v64, v65, vcc
	v_sqrt_f32_e32 v65, v64
	s_nop 0
	v_add_u32_e32 v66, -1, v65
	v_add_u32_e32 v67, 1, v65
	v_fma_f32 v68, -v66, v65, v64
	v_fma_f32 v69, -v67, v65, v64
	v_cmp_ge_f32_e64 s[0:1], 0, v68
	s_nop 1
	v_cndmask_b32_e64 v65, v65, v66, s[0:1]
	v_cmp_lt_f32_e64 s[0:1], 0, v69
	s_nop 1
	v_cndmask_b32_e64 v65, v65, v67, s[0:1]
	v_mul_f32_e32 v66, 0x37800000, v65
	v_cndmask_b32_e32 v65, v65, v66, vcc
	v_cmp_class_f32_e32 vcc, v64, v177
	s_nop 1
	v_cndmask_b32_e32 v64, v65, v64, vcc
	v_div_scale_f32 v65, s[0:1], v64, v64, 1.0
	v_rcp_f32_e32 v66, v65
	v_div_scale_f32 v67, vcc, 1.0, v64, 1.0
	s_lshl_b64 s[0:1], s[70:71], 11
	v_fma_f32 v68, -v65, v66, 1.0
	v_fmac_f32_e32 v66, v68, v66
	v_mul_f32_e32 v68, v67, v66
	v_fma_f32 v69, -v65, v68, v67
	v_fmac_f32_e32 v68, v69, v66
	v_fma_f32 v65, -v65, v68, v67
	v_div_fmas_f32 v65, v65, v66, v68
	v_div_fixup_f32 v64, v65, v64, 1.0
	v_pk_mul_f32 v[60:61], v[60:61], v[64:65] op_sel_hi:[1,0]
	v_pk_mul_f32 v[62:63], v[62:63], v[64:65] op_sel_hi:[1,0]
	v_pk_fma_f32 v[60:61], v[82:83], v[60:61], v[0:1]
	v_pk_fma_f32 v[62:63], v[80:81], v[62:63], v[2:3]
	v_bfe_u32 v65, v60, 16, 1
	v_add3_u32 v65, v60, v65, s59
	v_bfe_u32 v66, v61, 16, 1
	v_lshrrev_b32_e32 v65, 16, v65
	v_add3_u32 v66, v61, v66, s59
	v_and_or_b32 v68, v66, s60, v65
	v_bfe_u32 v65, v62, 16, 1
	v_add3_u32 v65, v62, v65, s59
	v_bfe_u32 v66, v63, 16, 1
	v_lshrrev_b32_e32 v65, 16, v65
	v_add3_u32 v66, v63, v66, s59
	v_and_or_b32 v69, v66, s60, v65
	v_cndmask_b32_e64 v65, 0, 1, s[68:69]
	v_lshl_add_u64 v[66:67], v[98:99], 0, s[0:1]
	v_cmp_ne_u32_e64 s[0:1], 1, v65
	s_andn2_b64 vcc, exec, s[68:69]
	global_store_dwordx2 v[66:67], v[68:69], off
	s_cbranch_vccnz .LBB0_174
	global_store_dwordx4 v[96:97], v[60:63], off

; __device__ __forceinline__ unsigned pk2(float lo, float hi) { return f2bf(lo) | (f2bf(hi) << 16); }
; __device__ __forceinline__ void norm_mod_phase(const float* x, const float* x0src, size_t x0stride, float* h0buf, const float* g, const float* sh, const float* sc, bf16* XN, int gw, int NGW, int lane) {
;     ...
;         for (int r = 0; r < 4; ++r) { const int t = wi + wpb * (k + r); const bool t0 = t == 0; const size_t row = (size_t)b * T + t;
;             float ss = 0.f;
; #pragma unroll
;             for (int j = 0; j < 4; ++j) ss += (v[r][j].x * v[r][j].x + v[r][j].y * v[r][j].y) + (v[r][j].z * v[r][j].z + v[r][j].w * v[r][j].w);
;             const float rstd = 1.f / sqrtf(wave_sum(ss) * (1.f / D) + EPS);
; #pragma unroll
;             for (int j = 0; j < 4; ++j) { const int col = 4 * lane + 256 * j;
;                 const f32x4 h = v[r][j] * rstd * gm[j] + s0[j];
;                 v2u o; o.x = pk2(h.x, h.y); o.y = pk2(h.z, h.w);
;                 *(v2u*)(XN + row * D + col) = o;
;                 if (t0) *(f32x4*)(h0buf + b * D + col) = h; } }
.LBB0_180:
	s_nop 0
	s_nop 0
	v_pk_mul_f32 v[48:49], v[46:47], v[46:47]
	v_pk_mul_f32 v[50:51], v[44:45], v[44:45]
	s_nop 0
	v_pk_mov_b32 v[52:53], v[50:51], v[48:49] op_sel:[1,0]
	v_mov_b32_e32 v51, v49
	v_pk_add_f32 v[48:49], v[52:53], v[50:51]
	s_nop 0
	v_pk_mul_f32 v[50:51], v[42:43], v[42:43]
	v_pk_mul_f32 v[52:53], v[40:41], v[40:41]
	v_pk_add_f32 v[48:49], v[48:49], v[48:49] op_sel:[0,1] op_sel_hi:[1,0]
	v_pk_mov_b32 v[54:55], v[52:53], v[50:51] op_sel:[1,0]
	v_mov_b32_e32 v53, v51
	v_pk_add_f32 v[50:51], v[54:55], v[52:53]
	s_nop 0
	v_mul_f32_e32 v52, v32, v32
	v_mul_f32_e32 v53, v33, v33
	v_pk_add_f32 v[50:51], v[50:51], v[50:51] op_sel:[0,1] op_sel_hi:[1,0]
	v_mov_b32_e32 v49, v52
	v_mov_b32_e32 v51, v53
	v_pk_add_f32 v[48:49], v[48:49], v[50:51]
	v_mul_f32_e32 v50, v37, v37
	v_mul_f32_e32 v52, v39, v39
	v_mul_f32_e32 v54, v34, v34
	v_mul_f32_e32 v55, v35, v35
	v_pk_fma_f32 v[50:51], v[36:37], v[36:37], v[50:51] op_sel_hi:[1,1,0]
	v_pk_fma_f32 v[52:53], v[38:39], v[38:39], v[52:53] op_sel_hi:[1,1,0]
	v_mov_b32_e32 v51, v54
	v_mov_b32_e32 v53, v55
	v_pk_add_f32 v[50:51], v[50:51], v[52:53]
	s_nop 0
	v_pk_add_f32 v[48:49], v[48:49], v[50:51]
	s_nop 0
	v_add_f32_e32 v48, v48, v49
	ds_bpermute_b32 v49, v104, v48
	s_waitcnt lgkmcnt(0)
	v_add_f32_e32 v48, v48, v49
	ds_bpermute_b32 v49, v105, v48
	s_waitcnt lgkmcnt(0)
	v_add_f32_e32 v48, v48, v49
	ds_bpermute_b32 v49, v106, v48
	s_waitcnt lgkmcnt(0)
	v_add_f32_e32 v48, v48, v49
	ds_bpermute_b32 v49, v107, v48
	s_waitcnt lgkmcnt(0)
	v_add_f32_e32 v48, v48, v49
	ds_bpermute_b32 v49, v108, v48
	s_waitcnt lgkmcnt(0)
	v_add_f32_e32 v48, v48, v49
	ds_bpermute_b32 v49, v109, v48
	s_waitcnt lgkmcnt(0)
	v_add_f32_e32 v48, v48, v49
	v_fmamk_f32 v48, v48, 0x3a800000, v161
	v_mul_f32_e32 v49, 0x4f800000, v48
	v_cmp_gt_f32_e32 vcc, s58, v48
	s_nop 1
	v_cndmask_b32_e32 v48, v48, v49, vcc
	v_sqrt_f32_e32 v49, v48
	s_nop 0
	v_add_u32_e32 v50, -1, v49
	v_add_u32_e32 v51, 1, v49
	v_fma_f32 v52, -v50, v49, v48
	v_fma_f32 v53, -v51, v49, v48
	v_cmp_ge_f32_e64 s[0:1], 0, v52
	s_nop 1
	v_cndmask_b32_e64 v49, v49, v50, s[0:1]
	v_cmp_lt_f32_e64 s[0:1], 0, v53
	s_nop 1
	v_cndmask_b32_e64 v49, v49, v51, s[0:1]
	v_mul_f32_e32 v50, 0x37800000, v49
	v_cndmask_b32_e32 v49, v49, v50, vcc
	v_cmp_class_f32_e32 vcc, v48, v177
	s_nop 1
	v_cndmask_b32_e32 v48, v49, v48, vcc
	v_div_scale_f32 v49, s[0:1], v48, v48, 1.0
	v_rcp_f32_e32 v50, v49
	v_div_scale_f32 v51, vcc, 1.0, v48, 1.0
	s_lshl_b64 s[0:1], s[66:67], 11
	v_fma_f32 v52, -v49, v50, 1.0
	v_fmac_f32_e32 v50, v52, v50
	v_mul_f32_e32 v52, v51, v50
	v_fma_f32 v53, -v49, v52, v51
	v_fmac_f32_e32 v52, v53, v50
	v_fma_f32 v49, -v49, v52, v51
	v_div_fmas_f32 v49, v49, v50, v52
	v_div_fixup_f32 v48, v49, v48, 1.0
	v_pk_mul_f32 v[44:45], v[44:45], v[48:49] op_sel_hi:[1,0]
	v_pk_mul_f32 v[46:47], v[46:47], v[48:49] op_sel_hi:[1,0]
	v_pk_fma_f32 v[44:45], v[82:83], v[44:45], v[0:1]
	v_pk_fma_f32 v[46:47], v[80:81], v[46:47], v[2:3]
	v_bfe_u32 v49, v44, 16, 1
	v_add3_u32 v49, v44, v49, s59
	v_bfe_u32 v50, v45, 16, 1
	v_lshrrev_b32_e32 v49, 16, v49
	v_add3_u32 v50, v45, v50, s59
	v_and_or_b32 v52, v50, s60, v49
	v_bfe_u32 v49, v46, 16, 1
	v_add3_u32 v49, v46, v49, s59
	v_bfe_u32 v50, v47, 16, 1
	v_lshrrev_b32_e32 v49, 16, v49
	v_add3_u32 v50, v47, v50, s59
	v_and_or_b32 v53, v50, s60, v49
	v_cndmask_b32_e64 v49, 0, 1, s[64:65]
	v_lshl_add_u64 v[50:51], v[98:99], 0, s[0:1]
	v_cmp_ne_u32_e64 s[0:1], 1, v49
	s_andn2_b64 vcc, exec, s[64:65]
	global_store_dwordx2 v[50:51], v[52:53], off
	s_cbranch_vccnz .LBB0_182
	global_store_dwordx4 v[96:97], v[44:47], off

; __device__ __forceinline__ unsigned pk2(float lo, float hi) { return f2bf(lo) | (f2bf(hi) << 16); }
; __device__ __forceinline__ void norm_mod_phase(const float* x, const float* x0src, size_t x0stride, float* h0buf, const float* g, const float* sh, const float* sc, bf16* XN, int gw, int NGW, int lane) {
;     ...
;         for (int r = 0; r < 4; ++r) { const int t = wi + wpb * (k + r); const bool t0 = t == 0; const size_t row = (size_t)b * T + t;
;             float ss = 0.f;
; #pragma unroll
;             for (int j = 0; j < 4; ++j) ss += (v[r][j].x * v[r][j].x + v[r][j].y * v[r][j].y) + (v[r][j].z * v[r][j].z + v[r][j].w * v[r][j].w);
;             const float rstd = 1.f / sqrtf(wave_sum(ss) * (1.f / D) + EPS);
; #pragma unroll
;             for (int j = 0; j < 4; ++j) { const int col = 4 * lane + 256 * j;
;                 const f32x4 h = v[r][j] * rstd * gm[j] + s0[j];
;                 v2u o; o.x = pk2(h.x, h.y); o.y = pk2(h.z, h.w);
;                 *(v2u*)(XN + row * D + col) = o;
;                 if (t0) *(f32x4*)(h0buf + b * D + col) = h; } }
.LBB0_188:
	s_nop 0
	s_nop 0
	v_pk_mul_f32 v[32:33], v[30:31], v[30:31]
	v_pk_mul_f32 v[34:35], v[28:29], v[28:29]
	s_nop 0
	v_pk_mov_b32 v[36:37], v[34:35], v[32:33] op_sel:[1,0]
	v_mov_b32_e32 v35, v33
	v_pk_add_f32 v[32:33], v[36:37], v[34:35]
	s_nop 0
	v_pk_mul_f32 v[34:35], v[26:27], v[26:27]
	v_pk_mul_f32 v[36:37], v[24:25], v[24:25]
	v_pk_add_f32 v[32:33], v[32:33], v[32:33] op_sel:[0,1] op_sel_hi:[1,0]
	v_pk_mov_b32 v[38:39], v[36:37], v[34:35] op_sel:[1,0]
	v_mov_b32_e32 v37, v35
	v_pk_add_f32 v[34:35], v[38:39], v[36:37]
	s_nop 0
	v_mul_f32_e32 v36, v16, v16
	v_mul_f32_e32 v37, v17, v17
	v_pk_add_f32 v[34:35], v[34:35], v[34:35] op_sel:[0,1] op_sel_hi:[1,0]
	v_mov_b32_e32 v33, v36
	v_mov_b32_e32 v35, v37
	v_pk_add_f32 v[32:33], v[32:33], v[34:35]
	v_mul_f32_e32 v34, v21, v21
	v_mul_f32_e32 v36, v23, v23
	v_mul_f32_e32 v38, v18, v18
	v_mul_f32_e32 v39, v19, v19
	v_pk_fma_f32 v[34:35], v[20:21], v[20:21], v[34:35] op_sel_hi:[1,1,0]
	v_pk_fma_f32 v[36:37], v[22:23], v[22:23], v[36:37] op_sel_hi:[1,1,0]
	v_mov_b32_e32 v35, v38
	v_mov_b32_e32 v37, v39
	v_pk_add_f32 v[34:35], v[34:35], v[36:37]
	s_nop 0
	v_pk_add_f32 v[32:33], v[32:33], v[34:35]
	s_nop 0
	v_add_f32_e32 v32, v32, v33
	ds_bpermute_b32 v33, v104, v32
	s_waitcnt lgkmcnt(0)
	v_add_f32_e32 v32, v32, v33
	ds_bpermute_b32 v33, v105, v32
	s_waitcnt lgkmcnt(0)
	v_add_f32_e32 v32, v32, v33
	ds_bpermute_b32 v33, v106, v32
	s_waitcnt lgkmcnt(0)
	v_add_f32_e32 v32, v32, v33
	ds_bpermute_b32 v33, v107, v32
	s_waitcnt lgkmcnt(0)
	v_add_f32_e32 v32, v32, v33
	ds_bpermute_b32 v33, v108, v32
	s_waitcnt lgkmcnt(0)
	v_add_f32_e32 v32, v32, v33
	ds_bpermute_b32 v33, v109, v32
	s_waitcnt lgkmcnt(0)
	v_add_f32_e32 v32, v32, v33
	v_fmamk_f32 v32, v32, 0x3a800000, v161
	v_mul_f32_e32 v33, 0x4f800000, v32
	v_cmp_gt_f32_e32 vcc, s58, v32
	s_nop 1
	v_cndmask_b32_e32 v32, v32, v33, vcc
	v_sqrt_f32_e32 v33, v32
	s_nop 0
	v_add_u32_e32 v34, -1, v33
	v_add_u32_e32 v35, 1, v33
	v_fma_f32 v36, -v34, v33, v32
	v_fma_f32 v37, -v35, v33, v32
	v_cmp_ge_f32_e64 s[0:1], 0, v36
	s_nop 1
	v_cndmask_b32_e64 v33, v33, v34, s[0:1]
	v_cmp_lt_f32_e64 s[0:1], 0, v37
	s_nop 1
	v_cndmask_b32_e64 v33, v33, v35, s[0:1]
	v_mul_f32_e32 v34, 0x37800000, v33
	v_cndmask_b32_e32 v33, v33, v34, vcc
	v_cmp_class_f32_e32 vcc, v32, v177
	s_nop 1
	v_cndmask_b32_e32 v32, v33, v32, vcc
	v_div_scale_f32 v33, s[0:1], v32, v32, 1.0
	v_rcp_f32_e32 v34, v33
	v_div_scale_f32 v35, vcc, 1.0, v32, 1.0
	s_lshl_b64 s[0:1], s[6:7], 11
	v_fma_f32 v36, -v33, v34, 1.0
	v_fmac_f32_e32 v34, v36, v34
	v_mul_f32_e32 v36, v35, v34
	v_fma_f32 v37, -v33, v36, v35
	v_fmac_f32_e32 v36, v37, v34
	v_fma_f32 v33, -v33, v36, v35
	v_div_fmas_f32 v33, v33, v34, v36
	v_div_fixup_f32 v32, v33, v32, 1.0
	v_pk_mul_f32 v[28:29], v[28:29], v[32:33] op_sel_hi:[1,0]
	v_pk_mul_f32 v[30:31], v[30:31], v[32:33] op_sel_hi:[1,0]
	v_pk_fma_f32 v[28:29], v[82:83], v[28:29], v[0:1]
	v_pk_fma_f32 v[30:31], v[80:81], v[30:31], v[2:3]
	v_bfe_u32 v33, v28, 16, 1
	v_add3_u32 v33, v28, v33, s59
	v_bfe_u32 v34, v29, 16, 1
	v_lshrrev_b32_e32 v33, 16, v33
	v_add3_u32 v34, v29, v34, s59
	v_and_or_b32 v36, v34, s60, v33
	v_bfe_u32 v33, v30, 16, 1
	v_add3_u32 v33, v30, v33, s59
	v_bfe_u32 v34, v31, 16, 1
	v_lshrrev_b32_e32 v33, 16, v33
	v_add3_u32 v34, v31, v34, s59
	v_and_or_b32 v37, v34, s60, v33
	v_cndmask_b32_e64 v33, 0, 1, s[4:5]
	v_lshl_add_u64 v[34:35], v[98:99], 0, s[0:1]
	v_cmp_ne_u32_e64 s[0:1], 1, v33
	s_andn2_b64 vcc, exec, s[4:5]
	global_store_dwordx2 v[34:35], v[36:37], off
	s_cbranch_vccnz .LBB0_190
	global_store_dwordx4 v[96:97], v[28:31], off

; __device__ __forceinline__ void norm_mod_phase(const float* x, const float* x0src, size_t x0stride, float* h0buf, const float* g, const float* sh, const float* sc, bf16* XN, int gw, int NGW, int lane) {
;     const int wpb = NGW / BATCH, rpw = T / wpb;
;     const int b = gw / wpb, wi = gw - b * wpb;
;     f32x4 gm[4], s0[4];
; #pragma unroll
;     for (int j = 0; j < 4; ++j) { const int col = 4 * lane + 256 * j; gm[j] = *(const f32x4*)(g + col) * (*(const f32x4*)(sc + b * NMOD + col) + 1.f); s0[j] = *(const f32x4*)(sh + b * NMOD + col); }
;     for (int k = 0; k < rpw; k += 4) {
.LBB0_1138:
	s_cmp_le_i32 s28, s8
	s_cselect_b64 s[2:3], -1, 0
	s_and_b64 s[0:1], s[2:3], s[0:1]
	s_andn2_b64 vcc, exec, s[0:1]
	s_cbranch_vccnz .LBB0_1174
	s_mov_b32 s4, s30
	s_mov_b32 s1, s10
	v_readlane_b32 s0, v255, 0
	v_readlane_b32 s3, v255, 11
	v_mov_b32_e32 v0, v160
	v_mov_b32_e32 v1, s0
	s_abs_i32 s0, s4
	v_mov_b32_e32 v6, s3
	ds_read2_b64 v[2:5], v1 offset1:1
	ds_read_b64 v[6:7], v6
	v_cvt_f32_u32_e32 v1, s0
	s_sub_i32 s7, 0, s0
	s_ashr_i32 s18, s4, 31
	v_readfirstlane_b32 s2, v0
	v_rcp_iflag_f32_e32 v1, v1
	s_waitcnt lgkmcnt(0)
	v_readfirstlane_b32 s5, v4
	v_readfirstlane_b32 s6, v5
	v_readfirstlane_b32 s16, v2
	v_mul_f32_e32 v1, 0x4f7ffffe, v1
	v_cvt_u32_f32_e32 v1, v1
	v_readfirstlane_b32 s17, v3
	v_readfirstlane_b32 s3, v6
	v_readfirstlane_b32 s20, v7
	v_readfirstlane_b32 s19, v1
	s_mul_i32 s7, s7, s19
	s_mul_hi_u32 s7, s19, s7
	s_add_i32 s19, s19, s7
	s_lshr_b32 s7, s19, 20
	s_mul_i32 s8, s7, s0
	s_sub_i32 s8, 0x1000, s8
	s_add_i32 s9, s7, 1
	s_sub_i32 s12, s8, s0
	s_cmp_ge_u32 s8, s0
	s_cselect_b32 s7, s9, s7
	s_cselect_b32 s8, s12, s8
	s_add_i32 s9, s7, 1
	s_cmp_ge_u32 s8, s0
	s_cselect_b32 s7, s9, s7
	s_xor_b32 s7, s7, s18
	s_sub_i32 s8, s7, s18
	s_cmp_lt_i32 s8, 1
	s_cbranch_scc1 .LBB0_1174
	s_mul_i32 s12, s62, 0xc000
	s_ashr_i32 s7, s2, 6
	s_lshl_b32 s9, s1, 3
	s_lshl_b32 s64, s62, 10
	s_add_i32 s1, s7, s9
	s_lshl_b64 s[66:67], s[12:13], 2
	s_mov_b32 s65, s13
	s_add_u32 s12, s5, s66
	s_addc_u32 s34, s6, s67
	s_lshl_b64 s[64:65], s[64:65], 2
	s_add_u32 s2, s3, s64
	s_addc_u32 s3, s20, s65
	s_ashr_i32 s20, s1, 31
	s_abs_i32 s1, s1
	s_mul_hi_u32 s19, s1, s19
	s_xor_b32 s18, s20, s18
	s_mul_i32 s20, s19, s0
	s_sub_i32 s1, s1, s20
	s_add_i32 s20, s19, 1
	s_sub_i32 s35, s1, s0
	s_cmp_ge_u32 s1, s0
	s_cselect_b32 s19, s20, s19
	s_cselect_b32 s1, s35, s1
	s_add_i32 s20, s19, 1
	s_cmp_ge_u32 s1, s0
	s_cselect_b32 s0, s20, s19
	s_xor_b32 s63, s0, s18
	s_sub_i32 s0, s63, s18
	s_mul_i32 s64, s0, 0x1800
	s_ashr_i32 s65, s64, 31
	s_lshl_b64 s[64:65], s[64:65], 2
	v_and_b32_e32 v16, 63, v0
	s_add_u32 s64, s12, s64
	s_addc_u32 s65, s34, s65
	v_lshlrev_b32_e32 v162, 4, v16
	v_lshl_add_u64 v[8:9], s[64:65], 0, v[162:163]
	s_movk_i32 s1, 0x4000
	v_add_co_u32_e32 v4, vcc, s1, v8
	global_load_dwordx4 v[0:3], v162, s[2:3]
	s_nop 0
	v_addc_co_u32_e32 v5, vcc, 0, v9, vcc
	global_load_dwordx4 v[4:7], v[4:5], off
	s_movk_i32 s1, 0x3000
	s_mov_b64 s[64:65], 0x4000
	v_lshl_add_u64 v[18:19], v[8:9], 0, s[64:65]
	s_mov_b64 s[64:65], 0x3000
	v_lshl_add_u64 v[22:23], v[8:9], 0, s[64:65]
	s_mul_i32 s19, s0, s4
	s_mov_b32 s12, 0
	v_lshlrev_b32_e32 v110, 4, v16
	s_waitcnt vmcnt(0)
	v_pk_add_f32 v[4:5], v[4:5], 1.0 op_sel_hi:[1,0]
	s_nop 0
	v_pk_mul_f32 v[82:83], v[0:1], v[4:5]
	v_add_co_u32_e32 v0, vcc, s1, v8
	v_pk_add_f32 v[6:7], v[6:7], 1.0 op_sel_hi:[1,0]
	s_nop 0
	v_addc_co_u32_e32 v1, vcc, 0, v9, vcc
	v_pk_mul_f32 v[80:81], v[2:3], v[6:7]
	global_load_dwordx4 v[0:3], v[0:1], off
	s_nop 0
	global_load_dwordx4 v[4:7], v162, s[2:3] offset:1024
	global_load_dwordx4 v[8:11], v[18:19], off offset:1024
	s_ashr_i32 s1, s0, 31
	v_cmp_lt_i32_e32 vcc, v228, v222
	s_waitcnt vmcnt(0)
	v_pk_add_f32 v[10:11], v[10:11], 1.0 op_sel_hi:[1,0]
	v_pk_add_f32 v[8:9], v[8:9], 1.0 op_sel_hi:[1,0]
	v_pk_mul_f32 v[84:85], v[6:7], v[10:11]
	v_pk_mul_f32 v[86:87], v[4:5], v[8:9]
	global_load_dwordx4 v[4:7], v[22:23], off offset:1024
	global_load_dwordx4 v[8:11], v162, s[2:3] offset:2048
	global_load_dwordx4 v[12:15], v[18:19], off offset:2048
	v_cndmask_b32_e32 v17, v221, v228, vcc
	v_lshlrev_b32_e32 v104, 2, v17
	v_xor_b32_e32 v17, 2, v221
	v_cmp_lt_i32_e32 vcc, v17, v222
	s_waitcnt vmcnt(0)
	v_pk_add_f32 v[14:15], v[14:15], 1.0 op_sel_hi:[1,0]
	v_pk_add_f32 v[12:13], v[12:13], 1.0 op_sel_hi:[1,0]
	v_pk_mul_f32 v[88:89], v[10:11], v[14:15]
	v_pk_mul_f32 v[90:91], v[8:9], v[12:13]
	global_load_dwordx4 v[8:11], v[22:23], off offset:2048
	global_load_dwordx4 v[12:15], v162, s[2:3] offset:3072
	s_nop 0
	global_load_dwordx4 v[18:21], v[18:19], off offset:3072
	s_lshl_b64 s[2:3], s[0:1], 24
	s_add_u32 s16, s16, s2
	s_addc_u32 s17, s17, s3
	s_lshl_b64 s[2:3], s[0:1], 12
	s_add_u32 s2, s5, s2
	s_addc_u32 s3, s6, s3
	s_add_u32 s20, s2, 0x590000
	s_addc_u32 s61, s3, 0
	s_lshl_b64 s[2:3], s[0:1], 23
	s_add_u32 s2, s5, s2
	s_addc_u32 s3, s6, s3
	s_lshl_b32 s0, s0, 10
	s_ashr_i32 s1, s0, 31
	s_lshl_b64 s[0:1], s[0:1], 2
	s_add_u32 s0, s5, s0
	s_addc_u32 s1, s6, s1
	v_cndmask_b32_e32 v17, v221, v17, vcc
	v_cmp_lt_i32_e32 vcc, v218, v222
	v_lshlrev_b32_e32 v105, 2, v17
	s_sub_i32 s76, s7, s19
	v_cndmask_b32_e32 v17, v221, v218, vcc
	v_cmp_lt_i32_e32 vcc, v219, v222
	v_lshlrev_b32_e32 v106, 2, v17
	s_waitcnt vmcnt(0)
	v_pk_add_f32 v[20:21], v[20:21], 1.0 op_sel_hi:[1,0]
	v_pk_add_f32 v[18:19], v[18:19], 1.0 op_sel_hi:[1,0]
	v_pk_mul_f32 v[92:93], v[14:15], v[20:21]
	v_pk_mul_f32 v[94:95], v[12:13], v[18:19]
	global_load_dwordx4 v[12:15], v[22:23], off offset:3072
	v_lshl_add_u64 v[18:19], s[0:1], 0, v[162:163]
	s_mov_b64 s[0:1], 0x598000
	v_lshlrev_b32_e32 v162, 3, v16
	v_lshl_add_u64 v[96:97], v[18:19], 0, s[0:1]
	v_lshl_add_u64 v[18:19], s[2:3], 0, v[162:163]
	s_mov_b64 s[0:1], 0x6e00000
	v_lshl_add_u64 v[98:99], v[18:19], 0, s[0:1]
	s_sub_i32 s0, s18, s63
	s_add_i32 s1, s0, 1
	v_cndmask_b32_e32 v17, v221, v219, vcc
	v_cmp_lt_i32_e32 vcc, v254, v222
	s_mul_i32 s1, s4, s1
	v_lshlrev_b32_e32 v107, 2, v17
	v_cndmask_b32_e32 v17, v221, v254, vcc
	v_cmp_lt_i32_e32 vcc, v223, v222
	s_add_i32 s18, s7, s1
	s_add_i32 s1, s0, 2
	s_add_i32 s0, s0, 3
	v_lshlrev_b32_e32 v108, 2, v17
	v_cndmask_b32_e32 v17, v221, v223, vcc
	s_lshl_b32 s63, s4, 2
	s_mul_i32 s1, s4, s1
	s_mul_i32 s4, s4, s0
	v_lshlrev_b32_e32 v109, 2, v17
	s_add_i32 s74, s7, s1
	s_add_i32 s75, s7, s4
	s_lshl_b32 s98, s63, 10
	s_mul_i32 s99, s98, 3
	v_add_u32_e32 v198, s99, v110
	s_add_i32 s99, s99, s98
	v_add_u32_e32 v199, s99, v110
	s_add_i32 s99, s99, s98
	v_add_u32_e32 v200, s99, v110
	s_add_i32 s99, s99, s98
	v_add_u32_e32 v201, s99, v110
	s_branch .LBB0_1142

; __device__ __forceinline__ void norm_mod_phase(const float* x, const float* x0src, size_t x0stride, float* h0buf, const float* g, const float* sh, const float* sc, bf16* XN, int gw, int NGW, int lane) {
;     ...
;     for (int k = 0; k < rpw; k += 4) {
;         f32x4 v[4][4];
; #pragma unroll
;         for (int r = 0; r < 4; ++r) { const int t = wi + wpb * (k + r); const bool t0 = t == 0;
;             const f32x4* xr = (const f32x4*)(t0 ? x0src + (size_t)b * x0stride : x + ((size_t)b * T + t) * D) + lane;
; #pragma unroll
;             for (int j = 0; j < 4; ++j) v[r][j] = xr[64 * j]; }
.LBB0_1142:
	s_add_i32 s0, s9, s76
	s_ashr_i32 s1, s0, 31
	s_lshl_b64 s[2:3], s[0:1], 12
	s_add_u32 s4, s16, s2
	s_addc_u32 s5, s17, s3
	s_cmp_eq_u32 s0, 0
	s_cselect_b64 s[70:71], -1, 0
	s_and_b64 s[2:3], s[70:71], exec
	s_cselect_b32 s72, s20, s4
	s_cselect_b32 s73, s61, s5
	s_add_i32 s68, s9, s18
	s_ashr_i32 s69, s68, 31
	s_lshl_b64 s[2:3], s[68:69], 12
	s_add_u32 s4, s16, s2
	s_addc_u32 s5, s17, s3
	s_cmp_eq_u32 s68, 0
	s_cselect_b64 s[66:67], -1, 0
	s_and_b64 s[2:3], s[66:67], exec
	s_cselect_b32 s78, s20, s4
	s_cselect_b32 s79, s61, s5
	s_add_i32 s64, s9, s74
	s_ashr_i32 s65, s64, 31
	s_lshl_b64 s[2:3], s[64:65], 12
	s_add_u32 s4, s16, s2
	s_addc_u32 s5, s17, s3
	s_cmp_eq_u32 s64, 0
	s_cselect_b64 s[6:7], -1, 0
	s_and_b64 s[2:3], s[6:7], exec
	s_cselect_b32 s80, s20, s4
	s_cselect_b32 s81, s61, s5
	s_add_i32 s4, s9, s75
	s_ashr_i32 s5, s4, 31
	s_lshl_b64 s[2:3], s[4:5], 12
	s_add_u32 s19, s16, s2
	s_addc_u32 s34, s17, s3
	s_cmp_eq_u32 s4, 0
	s_cselect_b64 s[2:3], -1, 0
	s_and_b64 s[82:83], s[2:3], exec
	s_cselect_b32 s82, s20, s19
	s_cselect_b32 s83, s61, s34
	s_cmp_lg_u32 s12, 0
	s_cbranch_scc1 .Lnp2_rest
	global_load_dwordx4 v[76:79], v110, s[72:73]
	global_load_dwordx4 v[72:75], v110, s[72:73] offset:1024
	global_load_dwordx4 v[68:71], v110, s[72:73] offset:2048
	global_load_dwordx4 v[64:67], v110, s[72:73] offset:3072
	global_load_dwordx4 v[60:63], v110, s[78:79]
	global_load_dwordx4 v[56:59], v110, s[78:79] offset:1024
	global_load_dwordx4 v[52:55], v110, s[78:79] offset:2048
	global_load_dwordx4 v[48:51], v110, s[78:79] offset:3072
	global_load_dwordx4 v[44:47], v110, s[80:81]
	global_load_dwordx4 v[40:43], v110, s[80:81] offset:1024
	global_load_dwordx4 v[36:39], v110, s[80:81] offset:2048
	global_load_dwordx4 v[32:35], v110, s[80:81] offset:3072
	global_load_dwordx4 v[28:31], v110, s[82:83]
	global_load_dwordx4 v[24:27], v110, s[82:83] offset:1024
	global_load_dwordx4 v[20:23], v110, s[82:83] offset:2048
	global_load_dwordx4 v[16:19], v110, s[82:83] offset:3072
	s_add_i32 s99, s12, 4
	s_cmp_lt_i32 s99, s8
	s_cbranch_scc0 .Lnp2_first_nopf
	global_load_dwordx4 v[194:197], v198, s[78:79]
	global_load_dwordx4 v[190:193], v198, s[78:79] offset:1024
	global_load_dwordx4 v[186:189], v198, s[78:79] offset:2048
	global_load_dwordx4 v[182:185], v198, s[78:79] offset:3072
	global_load_dwordx4 v[178:181], v199, s[78:79]
	global_load_dwordx4 v[156:159], v199, s[78:79] offset:1024
	global_load_dwordx4 v[152:155], v199, s[78:79] offset:2048
	global_load_dwordx4 v[148:151], v199, s[78:79] offset:3072
	global_load_dwordx4 v[144:147], v200, s[78:79]
	global_load_dwordx4 v[140:143], v200, s[78:79] offset:1024
	global_load_dwordx4 v[136:139], v200, s[78:79] offset:2048
	global_load_dwordx4 v[132:135], v200, s[78:79] offset:3072
	global_load_dwordx4 v[128:131], v201, s[78:79]
	global_load_dwordx4 v[124:127], v201, s[78:79] offset:1024
	global_load_dwordx4 v[120:123], v201, s[78:79] offset:2048
	global_load_dwordx4 v[116:119], v201, s[78:79] offset:3072
	s_waitcnt vmcnt(16)
	s_branch .Lnp2_go

; __device__ __forceinline__ unsigned pk2(float lo, float hi) { return f2bf(lo) | (f2bf(hi) << 16); }
; __device__ __forceinline__ void norm_mod_phase(const float* x, const float* x0src, size_t x0stride, float* h0buf, const float* g, const float* sh, const float* sc, bf16* XN, int gw, int NGW, int lane) {
;     ...
;     for (int k = 0; k < rpw; k += 4) {
;         f32x4 v[4][4];
; #pragma unroll
;         for (int r = 0; r < 4; ++r) { const int t = wi + wpb * (k + r); const bool t0 = t == 0;
;             const f32x4* xr = (const f32x4*)(t0 ? x0src + (size_t)b * x0stride : x + ((size_t)b * T + t) * D) + lane;
; #pragma unroll
;             for (int j = 0; j < 4; ++j) v[r][j] = xr[64 * j]; }
;         __builtin_amdgcn_sched_barrier(0);
; #pragma unroll
;         for (int r = 0; r < 4; ++r) { const int t = wi + wpb * (k + r); const bool t0 = t == 0; const size_t row = (size_t)b * T + t;
;             float ss = 0.f;
; #pragma unroll
;             for (int j = 0; j < 4; ++j) ss += (v[r][j].x * v[r][j].x + v[r][j].y * v[r][j].y) + (v[r][j].z * v[r][j].z + v[r][j].w * v[r][j].w);
;             const float rstd = 1.f / sqrtf(wave_sum(ss) * (1.f / D) + EPS);
; #pragma unroll
;             for (int j = 0; j < 4; ++j) { const int col = 4 * lane + 256 * j;
;                 const f32x4 h = v[r][j] * rstd * gm[j] + s0[j];
;                 v2u o; o.x = pk2(h.x, h.y); o.y = pk2(h.z, h.w);
;                 *(v2u*)(XN + row * D + col) = o;
;                 if (t0) *(f32x4*)(h0buf + b * D + col) = h; } }
.Lnp2_rest:
	s_waitcnt vmcnt(16)
	v_mov_b64_e32 v[16:17], v[116:117]
	v_mov_b64_e32 v[18:19], v[118:119]
	v_mov_b64_e32 v[20:21], v[120:121]
	v_mov_b64_e32 v[22:23], v[122:123]
	v_mov_b64_e32 v[24:25], v[124:125]
	v_mov_b64_e32 v[26:27], v[126:127]
	v_mov_b64_e32 v[28:29], v[128:129]
	v_mov_b64_e32 v[30:31], v[130:131]
	v_mov_b64_e32 v[32:33], v[132:133]
	v_mov_b64_e32 v[34:35], v[134:135]
	v_mov_b64_e32 v[36:37], v[136:137]
	v_mov_b64_e32 v[38:39], v[138:139]
	v_mov_b64_e32 v[40:41], v[140:141]
	v_mov_b64_e32 v[42:43], v[142:143]
	v_mov_b64_e32 v[44:45], v[144:145]
	v_mov_b64_e32 v[46:47], v[146:147]
	v_mov_b64_e32 v[48:49], v[148:149]
	v_mov_b64_e32 v[50:51], v[150:151]
	v_mov_b64_e32 v[52:53], v[152:153]
	v_mov_b64_e32 v[54:55], v[154:155]
	v_mov_b64_e32 v[56:57], v[156:157]
	v_mov_b64_e32 v[58:59], v[158:159]
	v_mov_b64_e32 v[60:61], v[178:179]
	v_mov_b64_e32 v[62:63], v[180:181]
	v_mov_b64_e32 v[64:65], v[182:183]
	v_mov_b64_e32 v[66:67], v[184:185]
	v_mov_b64_e32 v[68:69], v[186:187]
	v_mov_b64_e32 v[70:71], v[188:189]
	v_mov_b64_e32 v[72:73], v[190:191]
	v_mov_b64_e32 v[74:75], v[192:193]
	v_mov_b64_e32 v[76:77], v[194:195]
	v_mov_b64_e32 v[78:79], v[196:197]
	s_add_i32 s99, s12, 4
	s_cmp_lt_i32 s99, s8
	s_cbranch_scc0 .Lnp2_go
	global_load_dwordx4 v[194:197], v198, s[78:79]
	global_load_dwordx4 v[190:193], v198, s[78:79] offset:1024
	global_load_dwordx4 v[186:189], v198, s[78:79] offset:2048
	global_load_dwordx4 v[182:185], v198, s[78:79] offset:3072
	global_load_dwordx4 v[178:181], v199, s[78:79]
	global_load_dwordx4 v[156:159], v199, s[78:79] offset:1024
	global_load_dwordx4 v[152:155], v199, s[78:79] offset:2048
	global_load_dwordx4 v[148:151], v199, s[78:79] offset:3072
	global_load_dwordx4 v[144:147], v200, s[78:79]
	global_load_dwordx4 v[140:143], v200, s[78:79] offset:1024
	global_load_dwordx4 v[136:139], v200, s[78:79] offset:2048
	global_load_dwordx4 v[132:135], v200, s[78:79] offset:3072
	global_load_dwordx4 v[128:131], v201, s[78:79]
	global_load_dwordx4 v[124:127], v201, s[78:79] offset:1024
	global_load_dwordx4 v[120:123], v201, s[78:79] offset:2048
	global_load_dwordx4 v[116:119], v201, s[78:79] offset:3072
.Lnp2_go:
	s_lshl_b64 s[72:73], s[0:1], 11
	s_cmp_lg_u32 s0, 0
	s_nop 0
	v_pk_mul_f32 v[100:101], v[78:79], v[78:79]
	v_pk_mul_f32 v[102:103], v[76:77], v[76:77]
	s_nop 0
	v_mul_f32_e32 v111, v64, v64
	v_pk_mov_b32 v[112:113], v[102:103], v[100:101] op_sel:[1,0]
	v_mov_b32_e32 v103, v101
	v_pk_add_f32 v[100:101], v[112:113], v[102:103]
	v_pk_mul_f32 v[102:103], v[74:75], v[74:75]
	v_pk_mul_f32 v[112:113], v[72:73], v[72:73]
	v_pk_add_f32 v[100:101], v[100:101], v[100:101] op_sel:[0,1] op_sel_hi:[1,0]
	v_pk_mov_b32 v[114:115], v[112:113], v[102:103] op_sel:[1,0]
	v_mov_b32_e32 v113, v103
	v_pk_add_f32 v[102:103], v[114:115], v[112:113]
	v_mul_f32_e32 v112, v65, v65
	v_pk_add_f32 v[102:103], v[102:103], v[102:103] op_sel:[0,1] op_sel_hi:[1,0]
	v_mov_b32_e32 v101, v111
	v_mov_b32_e32 v103, v112
	v_pk_add_f32 v[100:101], v[100:101], v[102:103]
	v_mul_f32_e32 v102, v69, v69
	v_mul_f32_e32 v113, v66, v66
	v_pk_fma_f32 v[102:103], v[68:69], v[68:69], v[102:103] op_sel_hi:[1,1,0]
	v_mul_f32_e32 v112, v71, v71
	v_mul_f32_e32 v114, v67, v67
	v_mov_b32_e32 v103, v113
	v_pk_fma_f32 v[112:113], v[70:71], v[70:71], v[112:113] op_sel_hi:[1,1,0]
	s_nop 0
	v_mov_b32_e32 v113, v114
	v_pk_add_f32 v[102:103], v[102:103], v[112:113]
	s_nop 0
	v_pk_add_f32 v[100:101], v[100:101], v[102:103]
	s_nop 0
	v_add_f32_e32 v100, v100, v101
	ds_bpermute_b32 v101, v104, v100
	s_waitcnt lgkmcnt(0)
	v_add_f32_e32 v100, v100, v101
	ds_bpermute_b32 v101, v105, v100
	s_waitcnt lgkmcnt(0)
	v_add_f32_e32 v100, v100, v101
	ds_bpermute_b32 v101, v106, v100
	s_waitcnt lgkmcnt(0)
	v_add_f32_e32 v100, v100, v101
	ds_bpermute_b32 v101, v107, v100
	s_waitcnt lgkmcnt(0)
	v_add_f32_e32 v100, v100, v101
	ds_bpermute_b32 v101, v108, v100
	s_waitcnt lgkmcnt(0)
	v_add_f32_e32 v100, v100, v101
	ds_bpermute_b32 v101, v109, v100
	s_waitcnt lgkmcnt(0)
	v_add_f32_e32 v100, v100, v101
	v_fmamk_f32 v100, v100, 0x3a800000, v161
	v_mul_f32_e32 v101, 0x4f800000, v100
	v_cmp_gt_f32_e32 vcc, s58, v100
	s_nop 1
	v_cndmask_b32_e32 v100, v100, v101, vcc
	v_sqrt_f32_e32 v101, v100
	s_nop 0
	v_add_u32_e32 v102, -1, v101
	v_add_u32_e32 v103, 1, v101
	v_fma_f32 v111, -v102, v101, v100
	v_fma_f32 v112, -v103, v101, v100
	v_cmp_ge_f32_e64 s[0:1], 0, v111
	s_nop 1
	v_cndmask_b32_e64 v101, v101, v102, s[0:1]
	v_cmp_lt_f32_e64 s[0:1], 0, v112
	s_nop 1
	v_cndmask_b32_e64 v101, v101, v103, s[0:1]
	v_mul_f32_e32 v102, 0x37800000, v101
	v_cndmask_b32_e32 v101, v101, v102, vcc
	v_cmp_class_f32_e32 vcc, v100, v177
	s_nop 1
	v_cndmask_b32_e32 v100, v101, v100, vcc
	v_div_scale_f32 v101, s[0:1], v100, v100, 1.0
	v_rcp_f32_e32 v102, v101
	v_div_scale_f32 v103, vcc, 1.0, v100, 1.0
	v_fma_f32 v111, -v101, v102, 1.0
	v_fmac_f32_e32 v102, v111, v102
	v_mul_f32_e32 v111, v103, v102
	v_fma_f32 v112, -v101, v111, v103
	v_fmac_f32_e32 v111, v112, v102
	v_fma_f32 v101, -v101, v111, v103
	v_div_fmas_f32 v101, v101, v102, v111
	v_div_fixup_f32 v100, v101, v100, 1.0
	v_pk_mul_f32 v[76:77], v[76:77], v[100:101] op_sel_hi:[1,0]
	v_pk_mul_f32 v[78:79], v[78:79], v[100:101] op_sel_hi:[1,0]
	v_pk_fma_f32 v[76:77], v[82:83], v[76:77], v[0:1]
	v_pk_fma_f32 v[78:79], v[80:81], v[78:79], v[2:3]
	v_bfe_u32 v101, v76, 16, 1
	v_add3_u32 v101, v76, v101, s59
	v_bfe_u32 v102, v77, 16, 1
	v_lshrrev_b32_e32 v101, 16, v101
	v_add3_u32 v102, v77, v102, s59
	v_and_or_b32 v112, v102, s60, v101
	v_bfe_u32 v101, v78, 16, 1
	v_add3_u32 v101, v78, v101, s59
	v_bfe_u32 v102, v79, 16, 1
	v_lshrrev_b32_e32 v101, 16, v101
	v_add3_u32 v102, v79, v102, s59
	v_and_or_b32 v113, v102, s60, v101
	v_lshl_add_u64 v[102:103], v[98:99], 0, s[72:73]
	global_store_dwordx2 v[102:103], v[112:113], off
	s_cbranch_scc1 .LBB0_1144
	global_store_dwordx4 v[96:97], v[76:79], off

; __device__ __forceinline__ unsigned pk2(float lo, float hi) { return f2bf(lo) | (f2bf(hi) << 16); }
; __device__ __forceinline__ void norm_mod_phase(const float* x, const float* x0src, size_t x0stride, float* h0buf, const float* g, const float* sh, const float* sc, bf16* XN, int gw, int NGW, int lane) {
;     ...
;         for (int r = 0; r < 4; ++r) { const int t = wi + wpb * (k + r); const bool t0 = t == 0; const size_t row = (size_t)b * T + t;
;             float ss = 0.f;
; #pragma unroll
;             for (int j = 0; j < 4; ++j) ss += (v[r][j].x * v[r][j].x + v[r][j].y * v[r][j].y) + (v[r][j].z * v[r][j].z + v[r][j].w * v[r][j].w);
;             const float rstd = 1.f / sqrtf(wave_sum(ss) * (1.f / D) + EPS);
; #pragma unroll
;             for (int j = 0; j < 4; ++j) { const int col = 4 * lane + 256 * j;
;                 const f32x4 h = v[r][j] * rstd * gm[j] + s0[j];
;                 v2u o; o.x = pk2(h.x, h.y); o.y = pk2(h.z, h.w);
;                 *(v2u*)(XN + row * D + col) = o;
;                 if (t0) *(f32x4*)(h0buf + b * D + col) = h; } }
.LBB0_1150:
	s_nop 0
	s_nop 0
	v_pk_mul_f32 v[64:65], v[62:63], v[62:63]
	v_pk_mul_f32 v[66:67], v[60:61], v[60:61]
	s_nop 0
	v_pk_mov_b32 v[68:69], v[66:67], v[64:65] op_sel:[1,0]
	v_mov_b32_e32 v67, v65
	v_pk_add_f32 v[64:65], v[68:69], v[66:67]
	s_nop 0
	v_pk_mul_f32 v[66:67], v[58:59], v[58:59]
	v_pk_mul_f32 v[68:69], v[56:57], v[56:57]
	v_pk_add_f32 v[64:65], v[64:65], v[64:65] op_sel:[0,1] op_sel_hi:[1,0]
	v_pk_mov_b32 v[70:71], v[68:69], v[66:67] op_sel:[1,0]
	v_mov_b32_e32 v69, v67
	v_pk_add_f32 v[66:67], v[70:71], v[68:69]
	s_nop 0
	v_mul_f32_e32 v68, v48, v48
	v_mul_f32_e32 v69, v49, v49
	v_pk_add_f32 v[66:67], v[66:67], v[66:67] op_sel:[0,1] op_sel_hi:[1,0]
	v_mov_b32_e32 v65, v68
	v_mov_b32_e32 v67, v69
	v_pk_add_f32 v[64:65], v[64:65], v[66:67]
	v_mul_f32_e32 v66, v53, v53
	v_mul_f32_e32 v68, v55, v55
	v_mul_f32_e32 v70, v50, v50
	v_mul_f32_e32 v71, v51, v51
	v_pk_fma_f32 v[66:67], v[52:53], v[52:53], v[66:67] op_sel_hi:[1,1,0]
	v_pk_fma_f32 v[68:69], v[54:55], v[54:55], v[68:69] op_sel_hi:[1,1,0]
	v_mov_b32_e32 v67, v70
	v_mov_b32_e32 v69, v71
	v_pk_add_f32 v[66:67], v[66:67], v[68:69]
	s_nop 0
	v_pk_add_f32 v[64:65], v[64:65], v[66:67]
	s_nop 0
	v_add_f32_e32 v64, v64, v65
	ds_bpermute_b32 v65, v104, v64
	s_waitcnt lgkmcnt(0)
	v_add_f32_e32 v64, v64, v65
	ds_bpermute_b32 v65, v105, v64
	s_waitcnt lgkmcnt(0)
	v_add_f32_e32 v64, v64, v65
	ds_bpermute_b32 v65, v106, v64
	s_waitcnt lgkmcnt(0)
	v_add_f32_e32 v64, v64, v65
	ds_bpermute_b32 v65, v107, v64
	s_waitcnt lgkmcnt(0)
	v_add_f32_e32 v64, v64, v65
	ds_bpermute_b32 v65, v108, v64
	s_waitcnt lgkmcnt(0)
	v_add_f32_e32 v64, v64, v65
	ds_bpermute_b32 v65, v109, v64
	s_waitcnt lgkmcnt(0)
	v_add_f32_e32 v64, v64, v65
	v_fmamk_f32 v64, v64, 0x3a800000, v161
	v_mul_f32_e32 v65, 0x4f800000, v64
	v_cmp_gt_f32_e32 vcc, s58, v64
	s_nop 1
	v_cndmask_b32_e32 v64, v64, v65, vcc
	v_sqrt_f32_e32 v65, v64
	s_nop 0
	v_add_u32_e32 v66, -1, v65
	v_add_u32_e32 v67, 1, v65
	v_fma_f32 v68, -v66, v65, v64
	v_fma_f32 v69, -v67, v65, v64
	v_cmp_ge_f32_e64 s[0:1], 0, v68
	s_nop 1
	v_cndmask_b32_e64 v65, v65, v66, s[0:1]
	v_cmp_lt_f32_e64 s[0:1], 0, v69
	s_nop 1
	v_cndmask_b32_e64 v65, v65, v67, s[0:1]
	v_mul_f32_e32 v66, 0x37800000, v65
	v_cndmask_b32_e32 v65, v65, v66, vcc
	v_cmp_class_f32_e32 vcc, v64, v177
	s_nop 1
	v_cndmask_b32_e32 v64, v65, v64, vcc
	v_div_scale_f32 v65, s[0:1], v64, v64, 1.0
	v_rcp_f32_e32 v66, v65
	v_div_scale_f32 v67, vcc, 1.0, v64, 1.0
	s_lshl_b64 s[0:1], s[68:69], 11
	v_fma_f32 v68, -v65, v66, 1.0
	v_fmac_f32_e32 v66, v68, v66
	v_mul_f32_e32 v68, v67, v66
	v_fma_f32 v69, -v65, v68, v67
	v_fmac_f32_e32 v68, v69, v66
	v_fma_f32 v65, -v65, v68, v67
	v_div_fmas_f32 v65, v65, v66, v68
	v_div_fixup_f32 v64, v65, v64, 1.0
	v_pk_mul_f32 v[60:61], v[60:61], v[64:65] op_sel_hi:[1,0]
	v_pk_mul_f32 v[62:63], v[62:63], v[64:65] op_sel_hi:[1,0]
	v_pk_fma_f32 v[60:61], v[82:83], v[60:61], v[0:1]
	v_pk_fma_f32 v[62:63], v[80:81], v[62:63], v[2:3]
	v_bfe_u32 v65, v60, 16, 1
	v_add3_u32 v65, v60, v65, s59
	v_bfe_u32 v66, v61, 16, 1
	v_lshrrev_b32_e32 v65, 16, v65
	v_add3_u32 v66, v61, v66, s59
	v_and_or_b32 v68, v66, s60, v65
	v_bfe_u32 v65, v62, 16, 1
	v_add3_u32 v65, v62, v65, s59
	v_bfe_u32 v66, v63, 16, 1
	v_lshrrev_b32_e32 v65, 16, v65
	v_add3_u32 v66, v63, v66, s59
	v_and_or_b32 v69, v66, s60, v65
	v_cndmask_b32_e64 v65, 0, 1, s[66:67]
	v_lshl_add_u64 v[66:67], v[98:99], 0, s[0:1]
	v_cmp_ne_u32_e64 s[0:1], 1, v65
	s_andn2_b64 vcc, exec, s[66:67]
	global_store_dwordx2 v[66:67], v[68:69], off
	s_cbranch_vccnz .LBB0_1152
	global_store_dwordx4 v[96:97], v[60:63], off

; __device__ __forceinline__ unsigned pk2(float lo, float hi) { return f2bf(lo) | (f2bf(hi) << 16); }
; __device__ __forceinline__ void norm_mod_phase(const float* x, const float* x0src, size_t x0stride, float* h0buf, const float* g, const float* sh, const float* sc, bf16* XN, int gw, int NGW, int lane) {
;     ...
;         for (int r = 0; r < 4; ++r) { const int t = wi + wpb * (k + r); const bool t0 = t == 0; const size_t row = (size_t)b * T + t;
;             float ss = 0.f;
; #pragma unroll
;             for (int j = 0; j < 4; ++j) ss += (v[r][j].x * v[r][j].x + v[r][j].y * v[r][j].y) + (v[r][j].z * v[r][j].z + v[r][j].w * v[r][j].w);
;             const float rstd = 1.f / sqrtf(wave_sum(ss) * (1.f / D) + EPS);
; #pragma unroll
;             for (int j = 0; j < 4; ++j) { const int col = 4 * lane + 256 * j;
;                 const f32x4 h = v[r][j] * rstd * gm[j] + s0[j];
;                 v2u o; o.x = pk2(h.x, h.y); o.y = pk2(h.z, h.w);
;                 *(v2u*)(XN + row * D + col) = o;
;                 if (t0) *(f32x4*)(h0buf + b * D + col) = h; } }
.LBB0_1158:
	s_nop 0
	s_nop 0
	v_pk_mul_f32 v[48:49], v[46:47], v[46:47]
	v_pk_mul_f32 v[50:51], v[44:45], v[44:45]
	s_nop 0
	v_pk_mov_b32 v[52:53], v[50:51], v[48:49] op_sel:[1,0]
	v_mov_b32_e32 v51, v49
	v_pk_add_f32 v[48:49], v[52:53], v[50:51]
	s_nop 0
	v_pk_mul_f32 v[50:51], v[42:43], v[42:43]
	v_pk_mul_f32 v[52:53], v[40:41], v[40:41]
	v_pk_add_f32 v[48:49], v[48:49], v[48:49] op_sel:[0,1] op_sel_hi:[1,0]
	v_pk_mov_b32 v[54:55], v[52:53], v[50:51] op_sel:[1,0]
	v_mov_b32_e32 v53, v51
	v_pk_add_f32 v[50:51], v[54:55], v[52:53]
	s_nop 0
	v_mul_f32_e32 v52, v32, v32
	v_mul_f32_e32 v53, v33, v33
	v_pk_add_f32 v[50:51], v[50:51], v[50:51] op_sel:[0,1] op_sel_hi:[1,0]
	v_mov_b32_e32 v49, v52
	v_mov_b32_e32 v51, v53
	v_pk_add_f32 v[48:49], v[48:49], v[50:51]
	v_mul_f32_e32 v50, v37, v37
	v_mul_f32_e32 v52, v39, v39
	v_mul_f32_e32 v54, v34, v34
	v_mul_f32_e32 v55, v35, v35
	v_pk_fma_f32 v[50:51], v[36:37], v[36:37], v[50:51] op_sel_hi:[1,1,0]
	v_pk_fma_f32 v[52:53], v[38:39], v[38:39], v[52:53] op_sel_hi:[1,1,0]
	v_mov_b32_e32 v51, v54
	v_mov_b32_e32 v53, v55
	v_pk_add_f32 v[50:51], v[50:51], v[52:53]
	s_nop 0
	v_pk_add_f32 v[48:49], v[48:49], v[50:51]
	s_nop 0
	v_add_f32_e32 v48, v48, v49
	ds_bpermute_b32 v49, v104, v48
	s_waitcnt lgkmcnt(0)
	v_add_f32_e32 v48, v48, v49
	ds_bpermute_b32 v49, v105, v48
	s_waitcnt lgkmcnt(0)
	v_add_f32_e32 v48, v48, v49
	ds_bpermute_b32 v49, v106, v48
	s_waitcnt lgkmcnt(0)
	v_add_f32_e32 v48, v48, v49
	ds_bpermute_b32 v49, v107, v48
	s_waitcnt lgkmcnt(0)
	v_add_f32_e32 v48, v48, v49
	ds_bpermute_b32 v49, v108, v48
	s_waitcnt lgkmcnt(0)
	v_add_f32_e32 v48, v48, v49
	ds_bpermute_b32 v49, v109, v48
	s_waitcnt lgkmcnt(0)
	v_add_f32_e32 v48, v48, v49
	v_fmamk_f32 v48, v48, 0x3a800000, v161
	v_mul_f32_e32 v49, 0x4f800000, v48
	v_cmp_gt_f32_e32 vcc, s58, v48
	s_nop 1
	v_cndmask_b32_e32 v48, v48, v49, vcc
	v_sqrt_f32_e32 v49, v48
	s_nop 0
	v_add_u32_e32 v50, -1, v49
	v_add_u32_e32 v51, 1, v49
	v_fma_f32 v52, -v50, v49, v48
	v_fma_f32 v53, -v51, v49, v48
	v_cmp_ge_f32_e64 s[0:1], 0, v52
	s_nop 1
	v_cndmask_b32_e64 v49, v49, v50, s[0:1]
	v_cmp_lt_f32_e64 s[0:1], 0, v53
	s_nop 1
	v_cndmask_b32_e64 v49, v49, v51, s[0:1]
	v_mul_f32_e32 v50, 0x37800000, v49
	v_cndmask_b32_e32 v49, v49, v50, vcc
	v_cmp_class_f32_e32 vcc, v48, v177
	s_nop 1
	v_cndmask_b32_e32 v48, v49, v48, vcc
	v_div_scale_f32 v49, s[0:1], v48, v48, 1.0
	v_rcp_f32_e32 v50, v49
	v_div_scale_f32 v51, vcc, 1.0, v48, 1.0
	s_lshl_b64 s[0:1], s[64:65], 11
	v_fma_f32 v52, -v49, v50, 1.0
	v_fmac_f32_e32 v50, v52, v50
	v_mul_f32_e32 v52, v51, v50
	v_fma_f32 v53, -v49, v52, v51
	v_fmac_f32_e32 v52, v53, v50
	v_fma_f32 v49, -v49, v52, v51
	v_div_fmas_f32 v49, v49, v50, v52
	v_div_fixup_f32 v48, v49, v48, 1.0
	v_pk_mul_f32 v[44:45], v[44:45], v[48:49] op_sel_hi:[1,0]
	v_pk_mul_f32 v[46:47], v[46:47], v[48:49] op_sel_hi:[1,0]
	v_pk_fma_f32 v[44:45], v[82:83], v[44:45], v[0:1]
	v_pk_fma_f32 v[46:47], v[80:81], v[46:47], v[2:3]
	v_bfe_u32 v49, v44, 16, 1
	v_add3_u32 v49, v44, v49, s59
	v_bfe_u32 v50, v45, 16, 1
	v_lshrrev_b32_e32 v49, 16, v49
	v_add3_u32 v50, v45, v50, s59
	v_and_or_b32 v52, v50, s60, v49
	v_bfe_u32 v49, v46, 16, 1
	v_add3_u32 v49, v46, v49, s59
	v_bfe_u32 v50, v47, 16, 1
	v_lshrrev_b32_e32 v49, 16, v49
	v_add3_u32 v50, v47, v50, s59
	v_and_or_b32 v53, v50, s60, v49
	v_cndmask_b32_e64 v49, 0, 1, s[6:7]
	v_lshl_add_u64 v[50:51], v[98:99], 0, s[0:1]
	v_cmp_ne_u32_e64 s[0:1], 1, v49
	s_andn2_b64 vcc, exec, s[6:7]
	global_store_dwordx2 v[50:51], v[52:53], off
	s_cbranch_vccnz .LBB0_1160
	global_store_dwordx4 v[96:97], v[44:47], off

; __device__ __forceinline__ unsigned pk2(float lo, float hi) { return f2bf(lo) | (f2bf(hi) << 16); }
; __device__ __forceinline__ void norm_mod_phase(const float* x, const float* x0src, size_t x0stride, float* h0buf, const float* g, const float* sh, const float* sc, bf16* XN, int gw, int NGW, int lane) {
;     ...
;         for (int r = 0; r < 4; ++r) { const int t = wi + wpb * (k + r); const bool t0 = t == 0; const size_t row = (size_t)b * T + t;
;             float ss = 0.f;
; #pragma unroll
;             for (int j = 0; j < 4; ++j) ss += (v[r][j].x * v[r][j].x + v[r][j].y * v[r][j].y) + (v[r][j].z * v[r][j].z + v[r][j].w * v[r][j].w);
;             const float rstd = 1.f / sqrtf(wave_sum(ss) * (1.f / D) + EPS);
; #pragma unroll
;             for (int j = 0; j < 4; ++j) { const int col = 4 * lane + 256 * j;
;                 const f32x4 h = v[r][j] * rstd * gm[j] + s0[j];
;                 v2u o; o.x = pk2(h.x, h.y); o.y = pk2(h.z, h.w);
;                 *(v2u*)(XN + row * D + col) = o;
;                 if (t0) *(f32x4*)(h0buf + b * D + col) = h; } }
.LBB0_1166:
	s_nop 0
	s_nop 0
	v_pk_mul_f32 v[32:33], v[30:31], v[30:31]
	v_pk_mul_f32 v[34:35], v[28:29], v[28:29]
	s_nop 0
	v_pk_mov_b32 v[36:37], v[34:35], v[32:33] op_sel:[1,0]
	v_mov_b32_e32 v35, v33
	v_pk_add_f32 v[32:33], v[36:37], v[34:35]
	s_nop 0
	v_pk_mul_f32 v[34:35], v[26:27], v[26:27]
	v_pk_mul_f32 v[36:37], v[24:25], v[24:25]
	v_pk_add_f32 v[32:33], v[32:33], v[32:33] op_sel:[0,1] op_sel_hi:[1,0]
	v_pk_mov_b32 v[38:39], v[36:37], v[34:35] op_sel:[1,0]
	v_mov_b32_e32 v37, v35
	v_pk_add_f32 v[34:35], v[38:39], v[36:37]
	s_nop 0
	v_mul_f32_e32 v36, v16, v16
	v_mul_f32_e32 v37, v17, v17
	v_pk_add_f32 v[34:35], v[34:35], v[34:35] op_sel:[0,1] op_sel_hi:[1,0]
	v_mov_b32_e32 v33, v36
	v_mov_b32_e32 v35, v37
	v_pk_add_f32 v[32:33], v[32:33], v[34:35]
	v_mul_f32_e32 v34, v21, v21
	v_mul_f32_e32 v36, v23, v23
	v_mul_f32_e32 v38, v18, v18
	v_mul_f32_e32 v39, v19, v19
	v_pk_fma_f32 v[34:35], v[20:21], v[20:21], v[34:35] op_sel_hi:[1,1,0]
	v_pk_fma_f32 v[36:37], v[22:23], v[22:23], v[36:37] op_sel_hi:[1,1,0]
	v_mov_b32_e32 v35, v38
	v_mov_b32_e32 v37, v39
	v_pk_add_f32 v[34:35], v[34:35], v[36:37]
	s_nop 0
	v_pk_add_f32 v[32:33], v[32:33], v[34:35]
	s_nop 0
	v_add_f32_e32 v32, v32, v33
	ds_bpermute_b32 v33, v104, v32
	s_waitcnt lgkmcnt(0)
	v_add_f32_e32 v32, v32, v33
	ds_bpermute_b32 v33, v105, v32
	s_waitcnt lgkmcnt(0)
	v_add_f32_e32 v32, v32, v33
	ds_bpermute_b32 v33, v106, v32
	s_waitcnt lgkmcnt(0)
	v_add_f32_e32 v32, v32, v33
	ds_bpermute_b32 v33, v107, v32
	s_waitcnt lgkmcnt(0)
	v_add_f32_e32 v32, v32, v33
	ds_bpermute_b32 v33, v108, v32
	s_waitcnt lgkmcnt(0)
	v_add_f32_e32 v32, v32, v33
	ds_bpermute_b32 v33, v109, v32
	s_waitcnt lgkmcnt(0)
	v_add_f32_e32 v32, v32, v33
	v_fmamk_f32 v32, v32, 0x3a800000, v161
	v_mul_f32_e32 v33, 0x4f800000, v32
	v_cmp_gt_f32_e32 vcc, s58, v32
	s_nop 1
	v_cndmask_b32_e32 v32, v32, v33, vcc
	v_sqrt_f32_e32 v33, v32
	s_nop 0
	v_add_u32_e32 v34, -1, v33
	v_add_u32_e32 v35, 1, v33
	v_fma_f32 v36, -v34, v33, v32
	v_fma_f32 v37, -v35, v33, v32
	v_cmp_ge_f32_e64 s[0:1], 0, v36
	s_nop 1
	v_cndmask_b32_e64 v33, v33, v34, s[0:1]
	v_cmp_lt_f32_e64 s[0:1], 0, v37
	s_nop 1
	v_cndmask_b32_e64 v33, v33, v35, s[0:1]
	v_mul_f32_e32 v34, 0x37800000, v33
	v_cndmask_b32_e32 v33, v33, v34, vcc
	v_cmp_class_f32_e32 vcc, v32, v177
	s_nop 1
	v_cndmask_b32_e32 v32, v33, v32, vcc
	v_div_scale_f32 v33, s[0:1], v32, v32, 1.0
	v_rcp_f32_e32 v34, v33
	v_div_scale_f32 v35, vcc, 1.0, v32, 1.0
	s_lshl_b64 s[0:1], s[4:5], 11
	v_fma_f32 v36, -v33, v34, 1.0
	v_fmac_f32_e32 v34, v36, v34
	v_mul_f32_e32 v36, v35, v34
	v_fma_f32 v37, -v33, v36, v35
	v_fmac_f32_e32 v36, v37, v34
	v_fma_f32 v33, -v33, v36, v35
	v_div_fmas_f32 v33, v33, v34, v36
	v_div_fixup_f32 v32, v33, v32, 1.0
	v_pk_mul_f32 v[28:29], v[28:29], v[32:33] op_sel_hi:[1,0]
	v_pk_mul_f32 v[30:31], v[30:31], v[32:33] op_sel_hi:[1,0]
	v_pk_fma_f32 v[28:29], v[82:83], v[28:29], v[0:1]
	v_pk_fma_f32 v[30:31], v[80:81], v[30:31], v[2:3]
	v_bfe_u32 v33, v28, 16, 1
	v_add3_u32 v33, v28, v33, s59
	v_bfe_u32 v34, v29, 16, 1
	v_lshrrev_b32_e32 v33, 16, v33
	v_add3_u32 v34, v29, v34, s59
	v_and_or_b32 v36, v34, s60, v33
	v_bfe_u32 v33, v30, 16, 1
	v_add3_u32 v33, v30, v33, s59
	v_bfe_u32 v34, v31, 16, 1
	v_lshrrev_b32_e32 v33, 16, v33
	v_add3_u32 v34, v31, v34, s59
	v_and_or_b32 v37, v34, s60, v33
	v_cndmask_b32_e64 v33, 0, 1, s[2:3]
	v_lshl_add_u64 v[34:35], v[98:99], 0, s[0:1]
	v_cmp_ne_u32_e64 s[0:1], 1, v33
	s_andn2_b64 vcc, exec, s[2:3]
	global_store_dwordx2 v[34:35], v[36:37], off
	s_cbranch_vccnz .LBB0_1168
	global_store_dwordx4 v[96:97], v[28:31], off

; __global__ void __launch_bounds__(NTHR, 2) fwd_kernel(Args a) {
	.amdhsa_kernel _Z10fwd_kernel4Args
		.amdhsa_group_segment_fixed_size 0
		.amdhsa_private_segment_fixed_size 0
		.amdhsa_kernarg_size 384
		.amdhsa_user_sgpr_count 2
		.amdhsa_user_sgpr_dispatch_ptr 0
		.amdhsa_user_sgpr_queue_ptr 0
		.amdhsa_user_sgpr_kernarg_segment_ptr 1
		.amdhsa_user_sgpr_dispatch_id 0
		.amdhsa_user_sgpr_kernarg_preload_length 0
		.amdhsa_user_sgpr_kernarg_preload_offset 0
		.amdhsa_user_sgpr_private_segment_size 0
		.amdhsa_uses_dynamic_stack 0
		.amdhsa_enable_private_segment 0
		.amdhsa_system_sgpr_workgroup_id_x 1
		.amdhsa_system_sgpr_workgroup_id_y 0
		.amdhsa_system_sgpr_workgroup_id_z 0
		.amdhsa_system_sgpr_workgroup_info 0
		.amdhsa_system_vgpr_workitem_id 2
		.amdhsa_next_free_vgpr 256
		.amdhsa_next_free_sgpr 100
		.amdhsa_accum_offset 256
		.amdhsa_reserve_vcc 1
		.amdhsa_float_round_mode_32 0
		.amdhsa_float_round_mode_16_64 0
		.amdhsa_float_denorm_mode_32 3
		.amdhsa_float_denorm_mode_16_64 3
		.amdhsa_dx10_clamp 1
		.amdhsa_ieee_mode 1
		.amdhsa_fp16_overflow 0
		.amdhsa_tg_split 0
		.amdhsa_exception_fp_ieee_invalid_op 0
		.amdhsa_exception_fp_denorm_src 0
		.amdhsa_exception_fp_ieee_div_zero 0
		.amdhsa_exception_fp_ieee_overflow 0
		.amdhsa_exception_fp_ieee_underflow 0
		.amdhsa_exception_fp_ieee_inexact 0
		.amdhsa_exception_int_div_zero 0
	.end_amdhsa_kernel

; __global__ void __launch_bounds__(NTHR, 2) fwd_kernel(Args a) {
amdhsa.kernels:
  - .agpr_count:     0
    .args:
      - .offset:         0
        .size:           128
        .value_kind:     by_value
      - .offset:         128
        .size:           4
        .value_kind:     hidden_block_count_x
      - .offset:         132
        .size:           4
        .value_kind:     hidden_block_count_y
      - .offset:         136
        .size:           4
        .value_kind:     hidden_block_count_z
      - .offset:         140
        .size:           2
        .value_kind:     hidden_group_size_x
      - .offset:         142
        .size:           2
        .value_kind:     hidden_group_size_y
      - .offset:         144
        .size:           2
        .value_kind:     hidden_group_size_z
      - .offset:         146
        .size:           2
        .value_kind:     hidden_remainder_x
      - .offset:         148
        .size:           2
        .value_kind:     hidden_remainder_y
      - .offset:         150
        .size:           2
        .value_kind:     hidden_remainder_z
      - .offset:         168
        .size:           8
        .value_kind:     hidden_global_offset_x
      - .offset:         176
        .size:           8
        .value_kind:     hidden_global_offset_y
      - .offset:         184
        .size:           8
        .value_kind:     hidden_global_offset_z
      - .offset:         192
        .size:           2
        .value_kind:     hidden_grid_dims
      - .offset:         216
        .size:           8
        .value_kind:     hidden_multigrid_sync_arg
      - .offset:         248
        .size:           4
        .value_kind:     hidden_dynamic_lds_size
    .group_segment_fixed_size: 0
    .kernarg_segment_align: 8
    .kernarg_segment_size: 384
    .language:       OpenCL C
    .language_version:
      - 2
      - 0
    .max_flat_workgroup_size: 512
    .name:           _Z10fwd_kernel4Args
    .private_segment_fixed_size: 0
    .sgpr_count:     106
    .sgpr_spill_count: 16
    .symbol:         _Z10fwd_kernel4Args.kd
    .uniform_work_group_size: 1
    .uses_dynamic_stack: false
    .vgpr_count:     256
    .vgpr_spill_count: 0
    .wavefront_size: 64
